# P3 branch epilogue: gate loads hoisted above re-align barrier, counted vmcnt
# speedup vs baseline: 1.0071x; 1.0071x over previous
; #define PG8_STAGE(bufoff, gbase, voff) do { _Pragma("unroll") for (int _i = 0; _i < 2; ++_i) \
;         __builtin_amdgcn_global_load_lds((const __attribute__((address_space(1))) unsigned*)((const char*)(gbase) + (voff)[_i]), (LAS unsigned*)(lds + (bufoff) + ldsw + _i * 8192), 16, 0, 0); } while (0)
; #define PG8_LDA(dst, b, h) do { _Pragma("unroll") for (int m = 0; m < 4; ++m) _Pragma("unroll") for (int k = 0; k < 2; ++k) dst[m][k] = *(const LAS bf16x8*)(lds + PG8_SA(b, h) + aoff + m * 2048 + k * 1024); } while (0)
; #define PG8_LDB(dst, b, h) do { _Pragma("unroll") for (int n = 0; n < 2; ++n) _Pragma("unroll") for (int k = 0; k < 2; ++k) dst[n][k] = *(const LAS bf16x8*)(lds + PG8_SB(b, h) + boff + n * 2048 + k * 1024); } while (0)
; #define PG8_MMA(ai, bj, At, Bt) do { __builtin_amdgcn_s_setprio(1); _Pragma("unroll") for (int m = 0; m < 4; ++m) _Pragma("unroll") for (int n = 0; n < 2; ++n) _Pragma("unroll") for (int k = 0; k < 2; ++k) \
;         acc[ai][bj][m][n] = __builtin_amdgcn_mfma_f32_16x16x32_bf16(Bt[n][k], At[m][k], acc[ai][bj][m][n], 0, 0, 0); __builtin_amdgcn_s_setprio(0); } while (0)
; #define PG8_WAIT_V(n) asm volatile("s_waitcnt vmcnt(" #n ")" ::: "memory")
; #define PG8_WAIT_L(n) asm volatile("s_waitcnt lgkmcnt(" #n ")" ::: "memory")
; #define PG8_BAR __builtin_amdgcn_s_barrier()
; template <class Epi, class SchedT, bool ALIGN_EPI, bool SP2>
; __device__ __forceinline__ void gemm_phase(LAS unsigned char* lds, const int ldk, const int nt, const SchedT& S, const Epi& E) {
;     ...
;             const bool last = (t == nt - 2);
;             const char* a1 = cA + (size_t)(t + 1) * kstep;
;             const char* a2 = last ? nA : cA + (size_t)(t + 2) * kstep; const char* b2 = last ? nB : cB + (size_t)(t + 2) * kstep;
;             const char* a3 = a2 + kstep; const char* b3 = b2 + kstep;
;             if constexpr (SP2) {
;             PG8_LDB(B0, 0, 0); PG8_LDB(B1, 0, 1); PG8_SCHED; PG8_LDA(At, 0, 0); PG8_STAGE(PG8_SA(1, 1), a1 + hstep, voffA);
;             PG8_WAIT_V(8); PG8_WAIT_L(0); PG8_BAR; PG8_MMA(0, 0, At, B0); PG8_MMA(0, 1, At, B1); PG8_BAR; PG8_SCHED;
;             PG8_LDA(At, 0, 1); PG8_STAGE(PG8_SB(0, 0), b2, voffB); PG8_STAGE(PG8_SB(0, 1), b2 + hstepB, voffB); PG8_STAGE(PG8_SA(0, 0), a2, voffA);
;             PG8_WAIT_V(8); PG8_WAIT_L(0); PG8_BAR; PG8_MMA(1, 0, At, B0); PG8_MMA(1, 1, At, B1); PG8_BAR; PG8_SCHED;
.LBB0_534:
	s_add_u32 s36, s34, 0xfff80080
	s_addc_u32 s37, s35, -1
	s_add_i32 s49, 0, 0x10000
	s_cmp_eq_u32 s47, 12
	s_cselect_b32 s41, s1, s37
	s_cselect_b32 s40, s0, s36
	v_add_u32_e32 v0, s49, v159
	s_cselect_b32 s37, s53, s20
	s_cselect_b32 s36, s52, s17
	s_add_i32 s51, 0, 0x14000
	ds_read_b128 v[144:147], v0
	ds_read_b128 v[148:151], v0 offset:1024
	ds_read_b128 v[152:155], v0 offset:2048
	ds_read_b128 v[174:177], v0 offset:3072
	v_add_u32_e32 v0, s51, v159
	ds_read_b128 v[178:181], v0
	ds_read_b128 v[182:185], v0 offset:1024
	ds_read_b128 v[186:189], v0 offset:2048
	ds_read_b128 v[190:193], v0 offset:3072
	v_lshl_add_u64 v[2:3], s[34:35], 0, v[140:141]
	s_add_i32 m0, s57, 0xc000
	ds_read_b128 v[194:197], v161
	ds_read_b128 v[198:201], v161 offset:1024
	ds_read_b128 v[202:205], v161 offset:2048
	ds_read_b128 v[206:209], v161 offset:3072
	ds_read_b128 v[210:213], v161 offset:4096
	ds_read_b128 v[214:217], v161 offset:5120
	ds_read_b128 v[218:221], v161 offset:6144
	ds_read_b128 v[222:225], v161 offset:7168
	global_load_lds_dwordx4 v[2:3], off
	v_lshl_add_u64 v[2:3], s[34:35], 0, v[142:143]
	s_add_i32 m0, s57, 0xe000
	s_nop 0
	global_load_lds_dwordx4 v[2:3], off
	s_nop 0
	s_nop 0
	s_waitcnt vmcnt(8)
	s_waitcnt lgkmcnt(0)
	s_barrier
	s_setprio 1
	s_waitcnt lgkmcnt(0)
	v_mfma_f32_16x16x32_bf16 v[128:131], v[144:147], v[194:197], v[128:131]
	v_mfma_f32_16x16x32_bf16 v[124:127], v[152:155], v[194:197], v[124:127]
	v_mfma_f32_16x16x32_bf16 v[120:123], v[144:147], v[202:205], v[120:123]
	v_mfma_f32_16x16x32_bf16 v[116:119], v[152:155], v[202:205], v[116:119]
	v_mfma_f32_16x16x32_bf16 v[112:115], v[144:147], v[210:213], v[112:115]
	v_mfma_f32_16x16x32_bf16 v[108:111], v[152:155], v[210:213], v[108:111]
	v_mfma_f32_16x16x32_bf16 v[104:107], v[144:147], v[218:221], v[104:107]
	v_mfma_f32_16x16x32_bf16 v[100:103], v[152:155], v[218:221], v[100:103]
	v_mfma_f32_16x16x32_bf16 v[128:131], v[148:151], v[198:201], v[128:131]
	v_mfma_f32_16x16x32_bf16 v[124:127], v[174:177], v[198:201], v[124:127]
	v_mfma_f32_16x16x32_bf16 v[120:123], v[148:151], v[206:209], v[120:123]
	v_mfma_f32_16x16x32_bf16 v[116:119], v[174:177], v[206:209], v[116:119]
	v_mfma_f32_16x16x32_bf16 v[112:115], v[148:151], v[214:217], v[112:115]
	v_mfma_f32_16x16x32_bf16 v[108:111], v[174:177], v[214:217], v[108:111]
	v_mfma_f32_16x16x32_bf16 v[104:107], v[148:151], v[222:225], v[104:107]
	v_mfma_f32_16x16x32_bf16 v[100:103], v[174:177], v[222:225], v[100:103]
	s_setprio 0
	s_setprio 1
	v_mfma_f32_16x16x32_bf16 v[96:99], v[178:181], v[194:197], v[96:99]
	v_mfma_f32_16x16x32_bf16 v[92:95], v[186:189], v[194:197], v[92:95]
	v_mfma_f32_16x16x32_bf16 v[88:91], v[178:181], v[202:205], v[88:91]
	v_mfma_f32_16x16x32_bf16 v[84:87], v[186:189], v[202:205], v[84:87]
	v_mfma_f32_16x16x32_bf16 v[80:83], v[178:181], v[210:213], v[80:83]
	v_mfma_f32_16x16x32_bf16 v[76:79], v[186:189], v[210:213], v[76:79]
	v_mfma_f32_16x16x32_bf16 v[72:75], v[178:181], v[218:221], v[72:75]
	v_mfma_f32_16x16x32_bf16 v[68:71], v[186:189], v[218:221], v[68:71]
	v_mfma_f32_16x16x32_bf16 v[96:99], v[182:185], v[198:201], v[96:99]
	v_mfma_f32_16x16x32_bf16 v[92:95], v[190:193], v[198:201], v[92:95]
	v_mfma_f32_16x16x32_bf16 v[88:91], v[182:185], v[206:209], v[88:91]
	v_mfma_f32_16x16x32_bf16 v[84:87], v[190:193], v[206:209], v[84:87]
	v_mfma_f32_16x16x32_bf16 v[80:83], v[182:185], v[214:217], v[80:83]
	v_mfma_f32_16x16x32_bf16 v[76:79], v[190:193], v[214:217], v[76:79]
	v_mfma_f32_16x16x32_bf16 v[72:75], v[182:185], v[222:225], v[72:75]
	v_mfma_f32_16x16x32_bf16 v[68:71], v[190:193], v[222:225], v[68:71]
	s_setprio 0
	s_barrier
	s_add_i32 s49, s49, s56
	v_lshl_add_u64 v[156:157], s[36:37], 0, v[134:135]
	s_mov_b32 m0, s49
	ds_read_b128 v[194:197], v161 offset:16384
	ds_read_b128 v[198:201], v161 offset:17408
	ds_read_b128 v[202:205], v161 offset:18432
	ds_read_b128 v[206:209], v161 offset:19456
	ds_read_b128 v[210:213], v161 offset:20480
	ds_read_b128 v[214:217], v161 offset:21504
	ds_read_b128 v[218:221], v161 offset:22528
	ds_read_b128 v[222:225], v161 offset:23552
	global_load_lds_dwordx4 v[156:157], off
	s_add_i32 m0, s49, 0x2000
	s_add_u32 s82, s36, 0x20000
	v_lshl_add_u64 v[226:227], s[36:37], 0, v[138:139]
	s_addc_u32 s83, s37, 0
	s_add_i32 s49, s51, s56
	global_load_lds_dwordx4 v[226:227], off
	v_lshl_add_u64 v[2:3], s[82:83], 0, v[134:135]
	s_mov_b32 m0, s49
	v_lshl_add_u64 v[228:229], s[40:41], 0, v[132:133]
	global_load_lds_dwordx4 v[2:3], off
	v_lshl_add_u64 v[2:3], s[82:83], 0, v[138:139]
	s_add_i32 m0, s49, 0x2000
	v_lshl_add_u64 v[230:231], s[40:41], 0, v[136:137]
	global_load_lds_dwordx4 v[2:3], off
	s_mov_b32 m0, s57
	s_nop 0
	global_load_lds_dwordx4 v[228:229], off
	s_mov_b32 m0, s58
	s_nop 0
	global_load_lds_dwordx4 v[230:231], off
	s_waitcnt vmcnt(8)
	s_waitcnt lgkmcnt(0)
	s_barrier
; #define PG8_STAGE(bufoff, gbase, voff) do { _Pragma("unroll") for (int _i = 0; _i < 2; ++_i) \
;         __builtin_amdgcn_global_load_lds((const __attribute__((address_space(1))) unsigned*)((const char*)(gbase) + (voff)[_i]), (LAS unsigned*)(lds + (bufoff) + ldsw + _i * 8192), 16, 0, 0); } while (0)
; #define PG8_LDA(dst, b, h) do { _Pragma("unroll") for (int m = 0; m < 4; ++m) _Pragma("unroll") for (int k = 0; k < 2; ++k) dst[m][k] = *(const LAS bf16x8*)(lds + PG8_SA(b, h) + aoff + m * 2048 + k * 1024); } while (0)
; #define PG8_LDB(dst, b, h) do { _Pragma("unroll") for (int n = 0; n < 2; ++n) _Pragma("unroll") for (int k = 0; k < 2; ++k) dst[n][k] = *(const LAS bf16x8*)(lds + PG8_SB(b, h) + boff + n * 2048 + k * 1024); } while (0)
; #define PG8_MMA(ai, bj, At, Bt) do { __builtin_amdgcn_s_setprio(1); _Pragma("unroll") for (int m = 0; m < 4; ++m) _Pragma("unroll") for (int n = 0; n < 2; ++n) _Pragma("unroll") for (int k = 0; k < 2; ++k) \
;         acc[ai][bj][m][n] = __builtin_amdgcn_mfma_f32_16x16x32_bf16(Bt[n][k], At[m][k], acc[ai][bj][m][n], 0, 0, 0); __builtin_amdgcn_s_setprio(0); } while (0)
; #define PG8_WAIT_V(n) asm volatile("s_waitcnt vmcnt(" #n ")" ::: "memory")
; #define PG8_WAIT_L(n) asm volatile("s_waitcnt lgkmcnt(" #n ")" ::: "memory")
; #define PG8_BAR __builtin_amdgcn_s_barrier()
; #define PG8_SCHED __builtin_amdgcn_sched_barrier(0)
; template <class Epi, class SchedT, bool ALIGN_EPI, bool SP2>
; __device__ __forceinline__ void gemm_phase(LAS unsigned char* lds, const int ldk, const int nt, const SchedT& S, const Epi& E) {
;     ...
;             PG8_WAIT_V(8); PG8_WAIT_L(0); PG8_BAR; PG8_MMA(1, 0, At, B0); PG8_MMA(1, 1, At, B1); PG8_BAR; PG8_SCHED;
;             PG8_LDB(B0, 1, 0); PG8_LDB(B1, 1, 1); PG8_SCHED; PG8_LDA(At, 1, 0); PG8_STAGE(PG8_SA(0, 1), a2 + hstep, voffA);
;             PG8_WAIT_V(8); PG8_WAIT_L(0); PG8_BAR; PG8_MMA(0, 0, At, B0); PG8_MMA(0, 1, At, B1); PG8_BAR; PG8_SCHED;
	s_setprio 1
	s_waitcnt lgkmcnt(0)
	v_mfma_f32_16x16x32_bf16 v[64:67], v[144:147], v[194:197], v[64:67]
	v_mfma_f32_16x16x32_bf16 v[60:63], v[152:155], v[194:197], v[60:63]
	v_mfma_f32_16x16x32_bf16 v[56:59], v[144:147], v[202:205], v[56:59]
	v_mfma_f32_16x16x32_bf16 v[52:55], v[152:155], v[202:205], v[52:55]
	v_mfma_f32_16x16x32_bf16 v[48:51], v[144:147], v[210:213], v[48:51]
	v_mfma_f32_16x16x32_bf16 v[44:47], v[152:155], v[210:213], v[44:47]
	v_mfma_f32_16x16x32_bf16 v[40:43], v[144:147], v[218:221], v[40:43]
	v_mfma_f32_16x16x32_bf16 v[36:39], v[152:155], v[218:221], v[36:39]
	v_mfma_f32_16x16x32_bf16 v[64:67], v[148:151], v[198:201], v[64:67]
	v_mfma_f32_16x16x32_bf16 v[60:63], v[174:177], v[198:201], v[60:63]
	v_mfma_f32_16x16x32_bf16 v[56:59], v[148:151], v[206:209], v[56:59]
	v_mfma_f32_16x16x32_bf16 v[52:55], v[174:177], v[206:209], v[52:55]
	v_mfma_f32_16x16x32_bf16 v[48:51], v[148:151], v[214:217], v[48:51]
	v_mfma_f32_16x16x32_bf16 v[44:47], v[174:177], v[214:217], v[44:47]
	v_mfma_f32_16x16x32_bf16 v[40:43], v[148:151], v[222:225], v[40:43]
	v_mfma_f32_16x16x32_bf16 v[36:39], v[174:177], v[222:225], v[36:39]
	s_setprio 0
	s_setprio 1
	v_mfma_f32_16x16x32_bf16 v[32:35], v[178:181], v[194:197], v[32:35]
	v_mfma_f32_16x16x32_bf16 v[28:31], v[186:189], v[194:197], v[28:31]
	v_mfma_f32_16x16x32_bf16 v[24:27], v[178:181], v[202:205], v[24:27]
	v_mfma_f32_16x16x32_bf16 v[20:23], v[186:189], v[202:205], v[20:23]
	v_mfma_f32_16x16x32_bf16 v[16:19], v[178:181], v[210:213], v[16:19]
	v_mfma_f32_16x16x32_bf16 v[12:15], v[186:189], v[210:213], v[12:15]
	v_mfma_f32_16x16x32_bf16 v[8:11], v[178:181], v[218:221], v[8:11]
	v_mfma_f32_16x16x32_bf16 v[2:5], v[186:189], v[218:221], v[4:7]
	v_mfma_f32_16x16x32_bf16 v[32:35], v[182:185], v[198:201], v[32:35]
	v_mfma_f32_16x16x32_bf16 v[28:31], v[190:193], v[198:201], v[28:31]
	v_mfma_f32_16x16x32_bf16 v[24:27], v[182:185], v[206:209], v[24:27]
	v_mfma_f32_16x16x32_bf16 v[20:23], v[190:193], v[206:209], v[20:23]
	v_mfma_f32_16x16x32_bf16 v[16:19], v[182:185], v[214:217], v[16:19]
	v_mfma_f32_16x16x32_bf16 v[12:15], v[190:193], v[214:217], v[12:15]
	v_mfma_f32_16x16x32_bf16 v[8:11], v[182:185], v[222:225], v[8:11]
	v_mfma_f32_16x16x32_bf16 v[2:5], v[190:193], v[222:225], v[2:5]
	s_setprio 0
	s_barrier
	s_add_i32 s49, 0, 0x18000
	v_add_u32_e32 v0, s49, v159
	s_add_i32 s51, 0, 0x1c000
	ds_read_b128 v[144:147], v0
	ds_read_b128 v[148:151], v0 offset:1024
	ds_read_b128 v[152:155], v0 offset:2048
	ds_read_b128 v[174:177], v0 offset:3072
	v_add_u32_e32 v0, s51, v159
	ds_read_b128 v[178:181], v0
	ds_read_b128 v[182:185], v0 offset:1024
	ds_read_b128 v[186:189], v0 offset:2048
	ds_read_b128 v[190:193], v0 offset:3072
	s_add_u32 s40, s40, 0x80000
	s_addc_u32 s41, s41, 0
	s_mov_b32 m0, s59
	v_lshl_add_u64 v[6:7], s[40:41], 0, v[132:133]
	ds_read_b128 v[194:197], v161 offset:32768
	ds_read_b128 v[198:201], v161 offset:33792
	ds_read_b128 v[202:205], v161 offset:34816
	ds_read_b128 v[206:209], v161 offset:35840
	ds_read_b128 v[210:213], v161 offset:36864
	ds_read_b128 v[214:217], v161 offset:37888
	ds_read_b128 v[218:221], v161 offset:38912
	ds_read_b128 v[222:225], v161 offset:39936
	global_load_lds_dwordx4 v[6:7], off
	v_lshl_add_u64 v[6:7], s[40:41], 0, v[136:137]
	s_mov_b32 m0, s60
	s_nop 0
	global_load_lds_dwordx4 v[6:7], off
	s_nop 0
	s_waitcnt vmcnt(8)
	s_waitcnt lgkmcnt(0)
	s_barrier
	s_setprio 1
	s_waitcnt lgkmcnt(0)
	v_mfma_f32_16x16x32_bf16 v[128:131], v[144:147], v[194:197], v[128:131]
	v_mfma_f32_16x16x32_bf16 v[124:127], v[152:155], v[194:197], v[124:127]
	v_mfma_f32_16x16x32_bf16 v[120:123], v[144:147], v[202:205], v[120:123]
	v_mfma_f32_16x16x32_bf16 v[116:119], v[152:155], v[202:205], v[116:119]
	v_mfma_f32_16x16x32_bf16 v[112:115], v[144:147], v[210:213], v[112:115]
	v_mfma_f32_16x16x32_bf16 v[108:111], v[152:155], v[210:213], v[108:111]
	v_mfma_f32_16x16x32_bf16 v[104:107], v[144:147], v[218:221], v[104:107]
	v_mfma_f32_16x16x32_bf16 v[100:103], v[152:155], v[218:221], v[100:103]
	v_mfma_f32_16x16x32_bf16 v[128:131], v[148:151], v[198:201], v[128:131]
	v_mfma_f32_16x16x32_bf16 v[124:127], v[174:177], v[198:201], v[124:127]
	v_mfma_f32_16x16x32_bf16 v[120:123], v[148:151], v[206:209], v[120:123]
	v_mfma_f32_16x16x32_bf16 v[116:119], v[174:177], v[206:209], v[116:119]
	v_mfma_f32_16x16x32_bf16 v[112:115], v[148:151], v[214:217], v[112:115]
	v_mfma_f32_16x16x32_bf16 v[108:111], v[174:177], v[214:217], v[108:111]
	v_mfma_f32_16x16x32_bf16 v[104:107], v[148:151], v[222:225], v[104:107]
	v_mfma_f32_16x16x32_bf16 v[100:103], v[174:177], v[222:225], v[100:103]
	s_setprio 0
	s_setprio 1
	v_mfma_f32_16x16x32_bf16 v[96:99], v[178:181], v[194:197], v[96:99]
	v_mfma_f32_16x16x32_bf16 v[92:95], v[186:189], v[194:197], v[92:95]
	v_mfma_f32_16x16x32_bf16 v[88:91], v[178:181], v[202:205], v[88:91]
	v_mfma_f32_16x16x32_bf16 v[84:87], v[186:189], v[202:205], v[84:87]
	v_mfma_f32_16x16x32_bf16 v[80:83], v[178:181], v[210:213], v[80:83]
	v_mfma_f32_16x16x32_bf16 v[76:79], v[186:189], v[210:213], v[76:79]
	v_mfma_f32_16x16x32_bf16 v[72:75], v[178:181], v[218:221], v[72:75]
	v_mfma_f32_16x16x32_bf16 v[68:71], v[186:189], v[218:221], v[68:71]
	v_mfma_f32_16x16x32_bf16 v[96:99], v[182:185], v[198:201], v[96:99]
	v_mfma_f32_16x16x32_bf16 v[92:95], v[190:193], v[198:201], v[92:95]
	v_mfma_f32_16x16x32_bf16 v[88:91], v[182:185], v[206:209], v[88:91]
	v_mfma_f32_16x16x32_bf16 v[84:87], v[190:193], v[206:209], v[84:87]
	v_mfma_f32_16x16x32_bf16 v[80:83], v[182:185], v[214:217], v[80:83]
	v_mfma_f32_16x16x32_bf16 v[76:79], v[190:193], v[214:217], v[76:79]
	v_mfma_f32_16x16x32_bf16 v[72:75], v[182:185], v[222:225], v[72:75]
	v_mfma_f32_16x16x32_bf16 v[68:71], v[190:193], v[222:225], v[68:71]
	s_setprio 0
	s_barrier
; #define PG8_STAGE(bufoff, gbase, voff) do { _Pragma("unroll") for (int _i = 0; _i < 2; ++_i) \
;         __builtin_amdgcn_global_load_lds((const __attribute__((address_space(1))) unsigned*)((const char*)(gbase) + (voff)[_i]), (LAS unsigned*)(lds + (bufoff) + ldsw + _i * 8192), 16, 0, 0); } while (0)
; #define PG8_LDA(dst, b, h) do { _Pragma("unroll") for (int m = 0; m < 4; ++m) _Pragma("unroll") for (int k = 0; k < 2; ++k) dst[m][k] = *(const LAS bf16x8*)(lds + PG8_SA(b, h) + aoff + m * 2048 + k * 1024); } while (0)
; #define PG8_MMA(ai, bj, At, Bt) do { __builtin_amdgcn_s_setprio(1); _Pragma("unroll") for (int m = 0; m < 4; ++m) _Pragma("unroll") for (int n = 0; n < 2; ++n) _Pragma("unroll") for (int k = 0; k < 2; ++k) \
;         acc[ai][bj][m][n] = __builtin_amdgcn_mfma_f32_16x16x32_bf16(Bt[n][k], At[m][k], acc[ai][bj][m][n], 0, 0, 0); __builtin_amdgcn_s_setprio(0); } while (0)
; #define PG8_WAIT_V(n) asm volatile("s_waitcnt vmcnt(" #n ")" ::: "memory")
; #define PG8_WAIT_L(n) asm volatile("s_waitcnt lgkmcnt(" #n ")" ::: "memory")
; template <class Epi, class SchedT, bool ALIGN_EPI, bool SP2>
; __device__ __forceinline__ void gemm_phase(LAS unsigned char* lds, const int ldk, const int nt, const SchedT& S, const Epi& E) {
;     ...
;             PG8_LDA(At, 1, 1); PG8_STAGE(PG8_SB(1, 0), b3, voffB); PG8_STAGE(PG8_SB(1, 1), b3 + hstepB, voffB); PG8_STAGE(PG8_SA(1, 0), a3, voffA);
;             PG8_WAIT_V(8); PG8_WAIT_L(0); PG8_BAR; PG8_MMA(1, 0, At, B0); PG8_MMA(1, 1, At, B1); PG8_BAR; PG8_SCHED;
;     __device__ __forceinline__ void operator()(f32x4 (&acc)[2][2][4][2], const Unit& u, int wr, int wc, int fr, int fq) const {
;         const int row0 = u.pm * BM + wr * 64 + fr, col0 = u.pn * BM + wc * 64 + 8 * fq;
; #pragma unroll
;         for (int ai = 0; ai < 2; ++ai)
; #pragma unroll
;             for (int m = 0; m < 4; ++m) {
;                 const int row = row0 + ai * HALF + m * 16;
; #pragma unroll
;                 for (int bj = 0; bj < 2; ++bj) {
;                     const int col = col0 + bj * 32;
;                     const unsigned char* grow = (const unsigned char*)Gt + (size_t)row * 4096 + col;
;                     const u32x2 gw = *(const u32x2*)(grow + 2048);
;                     f32x4 g0 = gate_d4(gw.x), g1 = gate_d4(gw.y);
;                     if (u.kind == 0) {
;                         const u32x2 aw = *(const u32x2*)grow;
	s_add_i32 s40, s49, s56
	v_lshl_add_u64 v[6:7], v[156:157], 0, s[24:25]
	s_mov_b32 m0, s40
	ds_read_b128 v[194:197], v161 offset:49152
	ds_read_b128 v[198:201], v161 offset:50176
	ds_read_b128 v[202:205], v161 offset:51200
	ds_read_b128 v[206:209], v161 offset:52224
	ds_read_b128 v[210:213], v161 offset:53248
	ds_read_b128 v[214:217], v161 offset:54272
	ds_read_b128 v[218:221], v161 offset:55296
	ds_read_b128 v[222:225], v161 offset:56320
	global_load_lds_dwordx4 v[6:7], off
	s_add_i32 m0, s40, 0x2000
	s_add_u32 s36, s36, 0x20080
	v_lshl_add_u64 v[6:7], v[226:227], 0, s[24:25]
	s_addc_u32 s37, s37, 0
	s_add_i32 s40, s51, s56
	global_load_lds_dwordx4 v[6:7], off
	v_lshl_add_u64 v[6:7], s[36:37], 0, v[134:135]
	s_mov_b32 m0, s40
	s_nop 0
	global_load_lds_dwordx4 v[6:7], off
	v_lshl_add_u64 v[6:7], s[36:37], 0, v[138:139]
	s_add_i32 m0, s40, 0x2000
	s_nop 0
	global_load_lds_dwordx4 v[6:7], off
	v_lshl_add_u64 v[6:7], v[228:229], 0, s[24:25]
	s_mov_b32 m0, s61
	s_nop 0
	global_load_lds_dwordx4 v[6:7], off
	v_lshl_add_u64 v[6:7], v[230:231], 0, s[24:25]
	s_mov_b32 m0, s62
	s_nop 0
	global_load_lds_dwordx4 v[6:7], off
	s_waitcnt vmcnt(8)
	s_waitcnt lgkmcnt(0)
	s_barrier
	s_setprio 1
	s_waitcnt lgkmcnt(0)
	v_mfma_f32_16x16x32_bf16 v[64:67], v[144:147], v[194:197], v[64:67]
	v_mfma_f32_16x16x32_bf16 v[60:63], v[152:155], v[194:197], v[60:63]
	v_mfma_f32_16x16x32_bf16 v[56:59], v[144:147], v[202:205], v[56:59]
	v_mfma_f32_16x16x32_bf16 v[52:55], v[152:155], v[202:205], v[52:55]
	v_mfma_f32_16x16x32_bf16 v[48:51], v[144:147], v[210:213], v[48:51]
	v_mfma_f32_16x16x32_bf16 v[44:47], v[152:155], v[210:213], v[44:47]
	v_mfma_f32_16x16x32_bf16 v[40:43], v[144:147], v[218:221], v[40:43]
	v_mfma_f32_16x16x32_bf16 v[36:39], v[152:155], v[218:221], v[36:39]
	v_mfma_f32_16x16x32_bf16 v[64:67], v[148:151], v[198:201], v[64:67]
	v_mfma_f32_16x16x32_bf16 v[60:63], v[174:177], v[198:201], v[60:63]
	v_mfma_f32_16x16x32_bf16 v[56:59], v[148:151], v[206:209], v[56:59]
	v_mfma_f32_16x16x32_bf16 v[52:55], v[174:177], v[206:209], v[52:55]
	v_mfma_f32_16x16x32_bf16 v[48:51], v[148:151], v[214:217], v[48:51]
	v_mfma_f32_16x16x32_bf16 v[44:47], v[174:177], v[214:217], v[44:47]
	v_mfma_f32_16x16x32_bf16 v[40:43], v[148:151], v[222:225], v[40:43]
	v_mfma_f32_16x16x32_bf16 v[36:39], v[174:177], v[222:225], v[36:39]
	s_setprio 0
	s_setprio 1
	v_mfma_f32_16x16x32_bf16 v[32:35], v[178:181], v[194:197], v[32:35]
	v_mfma_f32_16x16x32_bf16 v[28:31], v[186:189], v[194:197], v[28:31]
	v_mfma_f32_16x16x32_bf16 v[24:27], v[178:181], v[202:205], v[24:27]
	v_mfma_f32_16x16x32_bf16 v[20:23], v[186:189], v[202:205], v[20:23]
	v_mfma_f32_16x16x32_bf16 v[16:19], v[178:181], v[210:213], v[16:19]
	v_mfma_f32_16x16x32_bf16 v[12:15], v[186:189], v[210:213], v[12:15]
	v_mfma_f32_16x16x32_bf16 v[6:9], v[178:181], v[218:221], v[8:11]
	v_mfma_f32_16x16x32_bf16 v[2:5], v[186:189], v[218:221], v[2:5]
	v_mfma_f32_16x16x32_bf16 v[32:35], v[182:185], v[198:201], v[32:35]
	v_mfma_f32_16x16x32_bf16 v[28:31], v[190:193], v[198:201], v[28:31]
	v_mfma_f32_16x16x32_bf16 v[24:27], v[182:185], v[206:209], v[24:27]
	v_mfma_f32_16x16x32_bf16 v[20:23], v[190:193], v[206:209], v[20:23]
	v_mfma_f32_16x16x32_bf16 v[16:19], v[182:185], v[214:217], v[16:19]
	v_mfma_f32_16x16x32_bf16 v[12:15], v[190:193], v[214:217], v[12:15]
	v_mfma_f32_16x16x32_bf16 v[8:11], v[182:185], v[222:225], v[6:9]
	v_mfma_f32_16x16x32_bf16 v[4:7], v[190:193], v[222:225], v[2:5]
	s_setprio 0
	s_barrier
	s_add_i32 s47, s47, 2
	s_add_u32 s34, s34, 0x100
	s_addc_u32 s35, s35, 0
	s_add_u32 s17, s17, 0x100
	s_addc_u32 s20, s20, 0
	s_cmp_gt_u32 s47, 13
	s_cbranch_scc0 .LBB0_534
	v_lshl_add_u32 v144, s16, 8, v158
	v_lshl_or_b32 v145, s12, 8, v160
	v_lshl_add_u32 v146, v144, 12, v145
	v_add_u32_e32 v147, 0x10000, v146
	v_add_u32_e32 v148, 0x20000, v146
	v_add_u32_e32 v149, 0x30000, v146
	v_add_u32_e32 v150, 0x80000, v146
	v_add_u32_e32 v151, 0x90000, v146
	v_add_u32_e32 v152, 0xa0000, v146
	v_add_u32_e32 v153, 0xb0000, v146
	s_cmp_lg_u32 s13, 0
	s_cbranch_scc1 .Lp3e_k1_loads
	global_load_dwordx2 v[174:175], v146, s[30:31] offset:2048
	global_load_dwordx2 v[176:177], v146, s[30:31] offset:0
	global_load_dwordx2 v[178:179], v146, s[30:31] offset:2080
	global_load_dwordx2 v[180:181], v146, s[30:31] offset:32
	global_load_dwordx2 v[182:183], v147, s[30:31] offset:2048
	global_load_dwordx2 v[184:185], v147, s[30:31] offset:0
	global_load_dwordx2 v[186:187], v147, s[30:31] offset:2080
	global_load_dwordx2 v[188:189], v147, s[30:31] offset:32
	global_load_dwordx2 v[190:191], v148, s[30:31] offset:2048
	global_load_dwordx2 v[192:193], v148, s[30:31] offset:0
	global_load_dwordx2 v[194:195], v148, s[30:31] offset:2080
	global_load_dwordx2 v[196:197], v148, s[30:31] offset:32
	global_load_dwordx2 v[198:199], v149, s[30:31] offset:2048
	global_load_dwordx2 v[200:201], v149, s[30:31] offset:0
	global_load_dwordx2 v[202:203], v149, s[30:31] offset:2080
	global_load_dwordx2 v[204:205], v149, s[30:31] offset:32
	global_load_dwordx2 v[206:207], v150, s[30:31] offset:2048
	global_load_dwordx2 v[208:209], v150, s[30:31] offset:0
	global_load_dwordx2 v[210:211], v150, s[30:31] offset:2080
	global_load_dwordx2 v[212:213], v150, s[30:31] offset:32
	global_load_dwordx2 v[214:215], v151, s[30:31] offset:2048
	global_load_dwordx2 v[216:217], v151, s[30:31] offset:0
	global_load_dwordx2 v[218:219], v151, s[30:31] offset:2080
	global_load_dwordx2 v[220:221], v151, s[30:31] offset:32
	global_load_dwordx2 v[222:223], v152, s[30:31] offset:2048
	global_load_dwordx2 v[224:225], v152, s[30:31] offset:0
	global_load_dwordx2 v[226:227], v152, s[30:31] offset:2080
	global_load_dwordx2 v[228:229], v152, s[30:31] offset:32
	global_load_dwordx2 v[230:231], v153, s[30:31] offset:2048
	global_load_dwordx2 v[232:233], v153, s[30:31] offset:0
	global_load_dwordx2 v[234:235], v153, s[30:31] offset:2080
	global_load_dwordx2 v[236:237], v153, s[30:31] offset:32
	s_branch .Lp3e_align
; __device__ __forceinline__ float fast_rcp(float x) { return __builtin_amdgcn_rcpf(x); }
; #define PG8_BAR __builtin_amdgcn_s_barrier()
; template <class Epi, class SchedT, bool ALIGN_EPI, bool SP2>
; __device__ __forceinline__ void gemm_phase(LAS unsigned char* lds, const int ldk, const int nt, const SchedT& S, const Epi& E) {
;     ...
;         if constexpr (ALIGN_EPI) { if (wr == 0) PG8_BAR; }
;     __device__ __forceinline__ void operator()(f32x4 (&acc)[2][2][4][2], const Unit& u, int wr, int wc, int fr, int fq) const {
;         const int row0 = u.pm * BM + wr * 64 + fr, col0 = u.pn * BM + wc * 64 + 8 * fq;
; #pragma unroll
;         for (int ai = 0; ai < 2; ++ai)
; #pragma unroll
;             for (int m = 0; m < 4; ++m) {
;                 const int row = row0 + ai * HALF + m * 16;
; #pragma unroll
;                 for (int bj = 0; bj < 2; ++bj) {
;                     const int col = col0 + bj * 32;
;                     const unsigned char* grow = (const unsigned char*)Gt + (size_t)row * 4096 + col;
;                     const u32x2 gw = *(const u32x2*)(grow + 2048);
;                     f32x4 g0 = gate_d4(gw.x), g1 = gate_d4(gw.y);
;                     if (u.kind == 0) {
;                         const u32x2 aw = *(const u32x2*)grow;
;                         const f32x4 a0 = gate_d4(aw.x), a1 = gate_d4(aw.y);
; #pragma unroll
;                         for (int j = 0; j < 4; ++j) { g0[j] = a0[j] * fast_rcp(g0[j]); g1[j] = a1[j] * fast_rcp(g1[j]); }
;                         acc[ai][bj][m][0] *= g0; acc[ai][bj][m][1] *= g1;
.Lp3e_k1_loads:
	global_load_dwordx2 v[174:175], v146, s[30:31] offset:2048
	global_load_dwordx2 v[176:177], v146, s[30:31] offset:2080
	global_load_dwordx2 v[178:179], v147, s[30:31] offset:2048
	global_load_dwordx2 v[180:181], v147, s[30:31] offset:2080
	global_load_dwordx2 v[182:183], v148, s[30:31] offset:2048
	global_load_dwordx2 v[184:185], v148, s[30:31] offset:2080
	global_load_dwordx2 v[186:187], v149, s[30:31] offset:2048
	global_load_dwordx2 v[188:189], v149, s[30:31] offset:2080
	global_load_dwordx2 v[190:191], v150, s[30:31] offset:2048
	global_load_dwordx2 v[192:193], v150, s[30:31] offset:2080
	global_load_dwordx2 v[194:195], v151, s[30:31] offset:2048
	global_load_dwordx2 v[196:197], v151, s[30:31] offset:2080
	global_load_dwordx2 v[198:199], v152, s[30:31] offset:2048
	global_load_dwordx2 v[200:201], v152, s[30:31] offset:2080
	global_load_dwordx2 v[202:203], v153, s[30:31] offset:2048
	global_load_dwordx2 v[204:205], v153, s[30:31] offset:2080
.Lp3e_align:
	s_and_b64 vcc, exec, s[44:45]
	s_cbranch_vccz .LBB0_537
	s_barrier
.LBB0_537:
	s_cmp_lg_u32 s13, 0
	s_cbranch_scc1 .Lp3e_k1
	s_waitcnt vmcnt(30)
	v_cvt_f32_ubyte0_e32 v246, v174
	v_cvt_f32_ubyte1_e32 v247, v174
	v_cvt_f32_ubyte2_e32 v248, v174
	v_cvt_f32_ubyte3_e32 v249, v174
	v_cvt_f32_ubyte0_e32 v250, v175
	v_cvt_f32_ubyte1_e32 v251, v175
	v_cvt_f32_ubyte2_e32 v252, v175
	v_cvt_f32_ubyte3_e32 v253, v175
	v_max_f32_e32 v246, 0.5, v246
	v_max_f32_e32 v247, 0.5, v247
	v_max_f32_e32 v248, 0.5, v248
	v_max_f32_e32 v249, 0.5, v249
	v_max_f32_e32 v250, 0.5, v250
	v_max_f32_e32 v251, 0.5, v251
	v_max_f32_e32 v252, 0.5, v252
	v_max_f32_e32 v253, 0.5, v253
	v_rcp_f32_e32 v246, v246
	v_rcp_f32_e32 v247, v247
	v_rcp_f32_e32 v248, v248
	v_rcp_f32_e32 v249, v249
	v_rcp_f32_e32 v250, v250
	v_rcp_f32_e32 v251, v251
	v_rcp_f32_e32 v252, v252
	v_rcp_f32_e32 v253, v253
	v_cvt_f32_ubyte0_e32 v238, v176
	v_cvt_f32_ubyte1_e32 v239, v176
	v_cvt_f32_ubyte2_e32 v154, v176
	v_cvt_f32_ubyte3_e32 v155, v176
	v_cvt_f32_ubyte0_e32 v156, v177
	v_cvt_f32_ubyte1_e32 v157, v177
	v_cvt_f32_ubyte2_e32 v2, v177
	v_cvt_f32_ubyte3_e32 v3, v177
	v_max_f32_e32 v238, 0.5, v238
	v_max_f32_e32 v239, 0.5, v239
	v_max_f32_e32 v154, 0.5, v154
	v_max_f32_e32 v155, 0.5, v155
	v_max_f32_e32 v156, 0.5, v156
	v_max_f32_e32 v157, 0.5, v157
	v_max_f32_e32 v2, 0.5, v2
	v_max_f32_e32 v3, 0.5, v3
	v_pk_mul_f32 v[246:247], v[238:239], v[246:247]
	v_pk_mul_f32 v[248:249], v[154:155], v[248:249]
	v_pk_mul_f32 v[250:251], v[156:157], v[250:251]
	v_pk_mul_f32 v[252:253], v[2:3], v[252:253]
	v_pk_mul_f32 v[128:129], v[128:129], v[246:247]
	v_pk_mul_f32 v[130:131], v[130:131], v[248:249]
	v_pk_mul_f32 v[124:125], v[124:125], v[250:251]
	v_pk_mul_f32 v[126:127], v[126:127], v[252:253]
	s_waitcnt vmcnt(28)
	v_cvt_f32_ubyte0_e32 v246, v178
	v_cvt_f32_ubyte1_e32 v247, v178
	v_cvt_f32_ubyte2_e32 v248, v178
	v_cvt_f32_ubyte3_e32 v249, v178
	v_cvt_f32_ubyte0_e32 v250, v179
	v_cvt_f32_ubyte1_e32 v251, v179
	v_cvt_f32_ubyte2_e32 v252, v179
	v_cvt_f32_ubyte3_e32 v253, v179
	v_max_f32_e32 v246, 0.5, v246
	v_max_f32_e32 v247, 0.5, v247
	v_max_f32_e32 v248, 0.5, v248
	v_max_f32_e32 v249, 0.5, v249
	v_max_f32_e32 v250, 0.5, v250
	v_max_f32_e32 v251, 0.5, v251
	v_max_f32_e32 v252, 0.5, v252
	v_max_f32_e32 v253, 0.5, v253
	v_rcp_f32_e32 v246, v246
	v_rcp_f32_e32 v247, v247
	v_rcp_f32_e32 v248, v248
	v_rcp_f32_e32 v249, v249
	v_rcp_f32_e32 v250, v250
	v_rcp_f32_e32 v251, v251
	v_rcp_f32_e32 v252, v252
	v_rcp_f32_e32 v253, v253
	v_cvt_f32_ubyte0_e32 v238, v180
	v_cvt_f32_ubyte1_e32 v239, v180
	v_cvt_f32_ubyte2_e32 v154, v180
	v_cvt_f32_ubyte3_e32 v155, v180
	v_cvt_f32_ubyte0_e32 v156, v181
	v_cvt_f32_ubyte1_e32 v157, v181
	v_cvt_f32_ubyte2_e32 v2, v181
	v_cvt_f32_ubyte3_e32 v3, v181
	v_max_f32_e32 v238, 0.5, v238
	v_max_f32_e32 v239, 0.5, v239
	v_max_f32_e32 v154, 0.5, v154
	v_max_f32_e32 v155, 0.5, v155
	v_max_f32_e32 v156, 0.5, v156
	v_max_f32_e32 v157, 0.5, v157
	v_max_f32_e32 v2, 0.5, v2
	v_max_f32_e32 v3, 0.5, v3
	v_pk_mul_f32 v[246:247], v[238:239], v[246:247]
	v_pk_mul_f32 v[248:249], v[154:155], v[248:249]
	v_pk_mul_f32 v[250:251], v[156:157], v[250:251]
	v_pk_mul_f32 v[252:253], v[2:3], v[252:253]
	v_pk_mul_f32 v[96:97], v[96:97], v[246:247]
	v_pk_mul_f32 v[98:99], v[98:99], v[248:249]
	v_pk_mul_f32 v[92:93], v[92:93], v[250:251]
	v_pk_mul_f32 v[94:95], v[94:95], v[252:253]
	s_waitcnt vmcnt(26)
	v_cvt_f32_ubyte0_e32 v246, v182
	v_cvt_f32_ubyte1_e32 v247, v182
	v_cvt_f32_ubyte2_e32 v248, v182
	v_cvt_f32_ubyte3_e32 v249, v182
	v_cvt_f32_ubyte0_e32 v250, v183
	v_cvt_f32_ubyte1_e32 v251, v183
	v_cvt_f32_ubyte2_e32 v252, v183
	v_cvt_f32_ubyte3_e32 v253, v183
	v_max_f32_e32 v246, 0.5, v246
	v_max_f32_e32 v247, 0.5, v247
	v_max_f32_e32 v248, 0.5, v248
	v_max_f32_e32 v249, 0.5, v249
	v_max_f32_e32 v250, 0.5, v250
	v_max_f32_e32 v251, 0.5, v251
	v_max_f32_e32 v252, 0.5, v252
	v_max_f32_e32 v253, 0.5, v253
	v_rcp_f32_e32 v246, v246
	v_rcp_f32_e32 v247, v247
	v_rcp_f32_e32 v248, v248
	v_rcp_f32_e32 v249, v249
	v_rcp_f32_e32 v250, v250
	v_rcp_f32_e32 v251, v251
	v_rcp_f32_e32 v252, v252
	v_rcp_f32_e32 v253, v253
	v_cvt_f32_ubyte0_e32 v238, v184
	v_cvt_f32_ubyte1_e32 v239, v184
	v_cvt_f32_ubyte2_e32 v154, v184
	v_cvt_f32_ubyte3_e32 v155, v184
	v_cvt_f32_ubyte0_e32 v156, v185
	v_cvt_f32_ubyte1_e32 v157, v185
	v_cvt_f32_ubyte2_e32 v2, v185
	v_cvt_f32_ubyte3_e32 v3, v185
	v_max_f32_e32 v238, 0.5, v238
	v_max_f32_e32 v239, 0.5, v239
	v_max_f32_e32 v154, 0.5, v154
	v_max_f32_e32 v155, 0.5, v155
	v_max_f32_e32 v156, 0.5, v156
	v_max_f32_e32 v157, 0.5, v157
	v_max_f32_e32 v2, 0.5, v2
	v_max_f32_e32 v3, 0.5, v3
	v_pk_mul_f32 v[246:247], v[238:239], v[246:247]
	v_pk_mul_f32 v[248:249], v[154:155], v[248:249]
	v_pk_mul_f32 v[250:251], v[156:157], v[250:251]
	v_pk_mul_f32 v[252:253], v[2:3], v[252:253]
	v_pk_mul_f32 v[120:121], v[120:121], v[246:247]
	v_pk_mul_f32 v[122:123], v[122:123], v[248:249]
	v_pk_mul_f32 v[116:117], v[116:117], v[250:251]
	v_pk_mul_f32 v[118:119], v[118:119], v[252:253]
	s_waitcnt vmcnt(24)
; __device__ __forceinline__ float fast_rcp(float x) { return __builtin_amdgcn_rcpf(x); }
;     __device__ __forceinline__ void operator()(f32x4 (&acc)[2][2][4][2], const Unit& u, int wr, int wc, int fr, int fq) const {
;     ...
;                 const int row = row0 + ai * HALF + m * 16;
; #pragma unroll
;                 for (int bj = 0; bj < 2; ++bj) {
;                     const int col = col0 + bj * 32;
;                     const unsigned char* grow = (const unsigned char*)Gt + (size_t)row * 4096 + col;
;                     const u32x2 gw = *(const u32x2*)(grow + 2048);
;                     f32x4 g0 = gate_d4(gw.x), g1 = gate_d4(gw.y);
;                     if (u.kind == 0) {
;                         const u32x2 aw = *(const u32x2*)grow;
;                         const f32x4 a0 = gate_d4(aw.x), a1 = gate_d4(aw.y);
; #pragma unroll
;                         for (int j = 0; j < 4; ++j) { g0[j] = a0[j] * fast_rcp(g0[j]); g1[j] = a1[j] * fast_rcp(g1[j]); }
;                         acc[ai][bj][m][0] *= g0; acc[ai][bj][m][1] *= g1;
	v_cvt_f32_ubyte0_e32 v246, v186
	v_cvt_f32_ubyte1_e32 v247, v186
	v_cvt_f32_ubyte2_e32 v248, v186
	v_cvt_f32_ubyte3_e32 v249, v186
	v_cvt_f32_ubyte0_e32 v250, v187
	v_cvt_f32_ubyte1_e32 v251, v187
	v_cvt_f32_ubyte2_e32 v252, v187
	v_cvt_f32_ubyte3_e32 v253, v187
	v_max_f32_e32 v246, 0.5, v246
	v_max_f32_e32 v247, 0.5, v247
	v_max_f32_e32 v248, 0.5, v248
	v_max_f32_e32 v249, 0.5, v249
	v_max_f32_e32 v250, 0.5, v250
	v_max_f32_e32 v251, 0.5, v251
	v_max_f32_e32 v252, 0.5, v252
	v_max_f32_e32 v253, 0.5, v253
	v_rcp_f32_e32 v246, v246
	v_rcp_f32_e32 v247, v247
	v_rcp_f32_e32 v248, v248
	v_rcp_f32_e32 v249, v249
	v_rcp_f32_e32 v250, v250
	v_rcp_f32_e32 v251, v251
	v_rcp_f32_e32 v252, v252
	v_rcp_f32_e32 v253, v253
	v_cvt_f32_ubyte0_e32 v238, v188
	v_cvt_f32_ubyte1_e32 v239, v188
	v_cvt_f32_ubyte2_e32 v154, v188
	v_cvt_f32_ubyte3_e32 v155, v188
	v_cvt_f32_ubyte0_e32 v156, v189
	v_cvt_f32_ubyte1_e32 v157, v189
	v_cvt_f32_ubyte2_e32 v2, v189
	v_cvt_f32_ubyte3_e32 v3, v189
	v_max_f32_e32 v238, 0.5, v238
	v_max_f32_e32 v239, 0.5, v239
	v_max_f32_e32 v154, 0.5, v154
	v_max_f32_e32 v155, 0.5, v155
	v_max_f32_e32 v156, 0.5, v156
	v_max_f32_e32 v157, 0.5, v157
	v_max_f32_e32 v2, 0.5, v2
	v_max_f32_e32 v3, 0.5, v3
	v_pk_mul_f32 v[246:247], v[238:239], v[246:247]
	v_pk_mul_f32 v[248:249], v[154:155], v[248:249]
	v_pk_mul_f32 v[250:251], v[156:157], v[250:251]
	v_pk_mul_f32 v[252:253], v[2:3], v[252:253]
	v_pk_mul_f32 v[88:89], v[88:89], v[246:247]
	v_pk_mul_f32 v[90:91], v[90:91], v[248:249]
	v_pk_mul_f32 v[84:85], v[84:85], v[250:251]
	v_pk_mul_f32 v[86:87], v[86:87], v[252:253]
	s_waitcnt vmcnt(22)
	v_cvt_f32_ubyte0_e32 v246, v190
	v_cvt_f32_ubyte1_e32 v247, v190
	v_cvt_f32_ubyte2_e32 v248, v190
	v_cvt_f32_ubyte3_e32 v249, v190
	v_cvt_f32_ubyte0_e32 v250, v191
	v_cvt_f32_ubyte1_e32 v251, v191
	v_cvt_f32_ubyte2_e32 v252, v191
	v_cvt_f32_ubyte3_e32 v253, v191
	v_max_f32_e32 v246, 0.5, v246
	v_max_f32_e32 v247, 0.5, v247
	v_max_f32_e32 v248, 0.5, v248
	v_max_f32_e32 v249, 0.5, v249
	v_max_f32_e32 v250, 0.5, v250
	v_max_f32_e32 v251, 0.5, v251
	v_max_f32_e32 v252, 0.5, v252
	v_max_f32_e32 v253, 0.5, v253
	v_rcp_f32_e32 v246, v246
	v_rcp_f32_e32 v247, v247
	v_rcp_f32_e32 v248, v248
	v_rcp_f32_e32 v249, v249
	v_rcp_f32_e32 v250, v250
	v_rcp_f32_e32 v251, v251
	v_rcp_f32_e32 v252, v252
	v_rcp_f32_e32 v253, v253
	v_cvt_f32_ubyte0_e32 v238, v192
	v_cvt_f32_ubyte1_e32 v239, v192
	v_cvt_f32_ubyte2_e32 v154, v192
	v_cvt_f32_ubyte3_e32 v155, v192
	v_cvt_f32_ubyte0_e32 v156, v193
	v_cvt_f32_ubyte1_e32 v157, v193
	v_cvt_f32_ubyte2_e32 v2, v193
	v_cvt_f32_ubyte3_e32 v3, v193
	v_max_f32_e32 v238, 0.5, v238
	v_max_f32_e32 v239, 0.5, v239
	v_max_f32_e32 v154, 0.5, v154
	v_max_f32_e32 v155, 0.5, v155
	v_max_f32_e32 v156, 0.5, v156
	v_max_f32_e32 v157, 0.5, v157
	v_max_f32_e32 v2, 0.5, v2
	v_max_f32_e32 v3, 0.5, v3
	v_pk_mul_f32 v[246:247], v[238:239], v[246:247]
	v_pk_mul_f32 v[248:249], v[154:155], v[248:249]
	v_pk_mul_f32 v[250:251], v[156:157], v[250:251]
	v_pk_mul_f32 v[252:253], v[2:3], v[252:253]
	v_pk_mul_f32 v[112:113], v[112:113], v[246:247]
	v_pk_mul_f32 v[114:115], v[114:115], v[248:249]
	v_pk_mul_f32 v[108:109], v[108:109], v[250:251]
	v_pk_mul_f32 v[110:111], v[110:111], v[252:253]
	s_waitcnt vmcnt(20)
	v_cvt_f32_ubyte0_e32 v246, v194
	v_cvt_f32_ubyte1_e32 v247, v194
	v_cvt_f32_ubyte2_e32 v248, v194
	v_cvt_f32_ubyte3_e32 v249, v194
	v_cvt_f32_ubyte0_e32 v250, v195
	v_cvt_f32_ubyte1_e32 v251, v195
	v_cvt_f32_ubyte2_e32 v252, v195
	v_cvt_f32_ubyte3_e32 v253, v195
	v_max_f32_e32 v246, 0.5, v246
	v_max_f32_e32 v247, 0.5, v247
	v_max_f32_e32 v248, 0.5, v248
	v_max_f32_e32 v249, 0.5, v249
	v_max_f32_e32 v250, 0.5, v250
	v_max_f32_e32 v251, 0.5, v251
	v_max_f32_e32 v252, 0.5, v252
	v_max_f32_e32 v253, 0.5, v253
	v_rcp_f32_e32 v246, v246
	v_rcp_f32_e32 v247, v247
	v_rcp_f32_e32 v248, v248
	v_rcp_f32_e32 v249, v249
	v_rcp_f32_e32 v250, v250
	v_rcp_f32_e32 v251, v251
	v_rcp_f32_e32 v252, v252
	v_rcp_f32_e32 v253, v253
	v_cvt_f32_ubyte0_e32 v238, v196
	v_cvt_f32_ubyte1_e32 v239, v196
	v_cvt_f32_ubyte2_e32 v154, v196
	v_cvt_f32_ubyte3_e32 v155, v196
	v_cvt_f32_ubyte0_e32 v156, v197
	v_cvt_f32_ubyte1_e32 v157, v197
	v_cvt_f32_ubyte2_e32 v2, v197
	v_cvt_f32_ubyte3_e32 v3, v197
	v_max_f32_e32 v238, 0.5, v238
	v_max_f32_e32 v239, 0.5, v239
	v_max_f32_e32 v154, 0.5, v154
	v_max_f32_e32 v155, 0.5, v155
	v_max_f32_e32 v156, 0.5, v156
	v_max_f32_e32 v157, 0.5, v157
	v_max_f32_e32 v2, 0.5, v2
	v_max_f32_e32 v3, 0.5, v3
	v_pk_mul_f32 v[246:247], v[238:239], v[246:247]
	v_pk_mul_f32 v[248:249], v[154:155], v[248:249]
	v_pk_mul_f32 v[250:251], v[156:157], v[250:251]
	v_pk_mul_f32 v[252:253], v[2:3], v[252:253]
	v_pk_mul_f32 v[80:81], v[80:81], v[246:247]
	v_pk_mul_f32 v[82:83], v[82:83], v[248:249]
	v_pk_mul_f32 v[76:77], v[76:77], v[250:251]
	v_pk_mul_f32 v[78:79], v[78:79], v[252:253]
	s_waitcnt vmcnt(18)
; __device__ __forceinline__ float fast_rcp(float x) { return __builtin_amdgcn_rcpf(x); }
;     __device__ __forceinline__ void operator()(f32x4 (&acc)[2][2][4][2], const Unit& u, int wr, int wc, int fr, int fq) const {
;     ...
;                 const int row = row0 + ai * HALF + m * 16;
; #pragma unroll
;                 for (int bj = 0; bj < 2; ++bj) {
;                     const int col = col0 + bj * 32;
;                     const unsigned char* grow = (const unsigned char*)Gt + (size_t)row * 4096 + col;
;                     const u32x2 gw = *(const u32x2*)(grow + 2048);
;                     f32x4 g0 = gate_d4(gw.x), g1 = gate_d4(gw.y);
;                     if (u.kind == 0) {
;                         const u32x2 aw = *(const u32x2*)grow;
;                         const f32x4 a0 = gate_d4(aw.x), a1 = gate_d4(aw.y);
; #pragma unroll
;                         for (int j = 0; j < 4; ++j) { g0[j] = a0[j] * fast_rcp(g0[j]); g1[j] = a1[j] * fast_rcp(g1[j]); }
;                         acc[ai][bj][m][0] *= g0; acc[ai][bj][m][1] *= g1;
	v_cvt_f32_ubyte0_e32 v246, v198
	v_cvt_f32_ubyte1_e32 v247, v198
	v_cvt_f32_ubyte2_e32 v248, v198
	v_cvt_f32_ubyte3_e32 v249, v198
	v_cvt_f32_ubyte0_e32 v250, v199
	v_cvt_f32_ubyte1_e32 v251, v199
	v_cvt_f32_ubyte2_e32 v252, v199
	v_cvt_f32_ubyte3_e32 v253, v199
	v_max_f32_e32 v246, 0.5, v246
	v_max_f32_e32 v247, 0.5, v247
	v_max_f32_e32 v248, 0.5, v248
	v_max_f32_e32 v249, 0.5, v249
	v_max_f32_e32 v250, 0.5, v250
	v_max_f32_e32 v251, 0.5, v251
	v_max_f32_e32 v252, 0.5, v252
	v_max_f32_e32 v253, 0.5, v253
	v_rcp_f32_e32 v246, v246
	v_rcp_f32_e32 v247, v247
	v_rcp_f32_e32 v248, v248
	v_rcp_f32_e32 v249, v249
	v_rcp_f32_e32 v250, v250
	v_rcp_f32_e32 v251, v251
	v_rcp_f32_e32 v252, v252
	v_rcp_f32_e32 v253, v253
	v_cvt_f32_ubyte0_e32 v238, v200
	v_cvt_f32_ubyte1_e32 v239, v200
	v_cvt_f32_ubyte2_e32 v154, v200
	v_cvt_f32_ubyte3_e32 v155, v200
	v_cvt_f32_ubyte0_e32 v156, v201
	v_cvt_f32_ubyte1_e32 v157, v201
	v_cvt_f32_ubyte2_e32 v2, v201
	v_cvt_f32_ubyte3_e32 v3, v201
	v_max_f32_e32 v238, 0.5, v238
	v_max_f32_e32 v239, 0.5, v239
	v_max_f32_e32 v154, 0.5, v154
	v_max_f32_e32 v155, 0.5, v155
	v_max_f32_e32 v156, 0.5, v156
	v_max_f32_e32 v157, 0.5, v157
	v_max_f32_e32 v2, 0.5, v2
	v_max_f32_e32 v3, 0.5, v3
	v_pk_mul_f32 v[246:247], v[238:239], v[246:247]
	v_pk_mul_f32 v[248:249], v[154:155], v[248:249]
	v_pk_mul_f32 v[250:251], v[156:157], v[250:251]
	v_pk_mul_f32 v[252:253], v[2:3], v[252:253]
	v_pk_mul_f32 v[104:105], v[104:105], v[246:247]
	v_pk_mul_f32 v[106:107], v[106:107], v[248:249]
	v_pk_mul_f32 v[100:101], v[100:101], v[250:251]
	v_pk_mul_f32 v[102:103], v[102:103], v[252:253]
	s_waitcnt vmcnt(16)
	v_cvt_f32_ubyte0_e32 v246, v202
	v_cvt_f32_ubyte1_e32 v247, v202
	v_cvt_f32_ubyte2_e32 v248, v202
	v_cvt_f32_ubyte3_e32 v249, v202
	v_cvt_f32_ubyte0_e32 v250, v203
	v_cvt_f32_ubyte1_e32 v251, v203
	v_cvt_f32_ubyte2_e32 v252, v203
	v_cvt_f32_ubyte3_e32 v253, v203
	v_max_f32_e32 v246, 0.5, v246
	v_max_f32_e32 v247, 0.5, v247
	v_max_f32_e32 v248, 0.5, v248
	v_max_f32_e32 v249, 0.5, v249
	v_max_f32_e32 v250, 0.5, v250
	v_max_f32_e32 v251, 0.5, v251
	v_max_f32_e32 v252, 0.5, v252
	v_max_f32_e32 v253, 0.5, v253
	v_rcp_f32_e32 v246, v246
	v_rcp_f32_e32 v247, v247
	v_rcp_f32_e32 v248, v248
	v_rcp_f32_e32 v249, v249
	v_rcp_f32_e32 v250, v250
	v_rcp_f32_e32 v251, v251
	v_rcp_f32_e32 v252, v252
	v_rcp_f32_e32 v253, v253
	v_cvt_f32_ubyte0_e32 v238, v204
	v_cvt_f32_ubyte1_e32 v239, v204
	v_cvt_f32_ubyte2_e32 v154, v204
	v_cvt_f32_ubyte3_e32 v155, v204
	v_cvt_f32_ubyte0_e32 v156, v205
	v_cvt_f32_ubyte1_e32 v157, v205
	v_cvt_f32_ubyte2_e32 v2, v205
	v_cvt_f32_ubyte3_e32 v3, v205
	v_max_f32_e32 v238, 0.5, v238
	v_max_f32_e32 v239, 0.5, v239
	v_max_f32_e32 v154, 0.5, v154
	v_max_f32_e32 v155, 0.5, v155
	v_max_f32_e32 v156, 0.5, v156
	v_max_f32_e32 v157, 0.5, v157
	v_max_f32_e32 v2, 0.5, v2
	v_max_f32_e32 v3, 0.5, v3
	v_pk_mul_f32 v[246:247], v[238:239], v[246:247]
	v_pk_mul_f32 v[248:249], v[154:155], v[248:249]
	v_pk_mul_f32 v[250:251], v[156:157], v[250:251]
	v_pk_mul_f32 v[252:253], v[2:3], v[252:253]
	v_pk_mul_f32 v[72:73], v[72:73], v[246:247]
	v_pk_mul_f32 v[74:75], v[74:75], v[248:249]
	v_pk_mul_f32 v[68:69], v[68:69], v[250:251]
	v_pk_mul_f32 v[70:71], v[70:71], v[252:253]
	s_waitcnt vmcnt(14)
	v_cvt_f32_ubyte0_e32 v246, v206
	v_cvt_f32_ubyte1_e32 v247, v206
	v_cvt_f32_ubyte2_e32 v248, v206
	v_cvt_f32_ubyte3_e32 v249, v206
	v_cvt_f32_ubyte0_e32 v250, v207
	v_cvt_f32_ubyte1_e32 v251, v207
	v_cvt_f32_ubyte2_e32 v252, v207
	v_cvt_f32_ubyte3_e32 v253, v207
	v_max_f32_e32 v246, 0.5, v246
	v_max_f32_e32 v247, 0.5, v247
	v_max_f32_e32 v248, 0.5, v248
	v_max_f32_e32 v249, 0.5, v249
	v_max_f32_e32 v250, 0.5, v250
	v_max_f32_e32 v251, 0.5, v251
	v_max_f32_e32 v252, 0.5, v252
	v_max_f32_e32 v253, 0.5, v253
	v_rcp_f32_e32 v246, v246
	v_rcp_f32_e32 v247, v247
	v_rcp_f32_e32 v248, v248
	v_rcp_f32_e32 v249, v249
	v_rcp_f32_e32 v250, v250
	v_rcp_f32_e32 v251, v251
	v_rcp_f32_e32 v252, v252
	v_rcp_f32_e32 v253, v253
	v_cvt_f32_ubyte0_e32 v238, v208
	v_cvt_f32_ubyte1_e32 v239, v208
	v_cvt_f32_ubyte2_e32 v154, v208
	v_cvt_f32_ubyte3_e32 v155, v208
	v_cvt_f32_ubyte0_e32 v156, v209
	v_cvt_f32_ubyte1_e32 v157, v209
	v_cvt_f32_ubyte2_e32 v2, v209
	v_cvt_f32_ubyte3_e32 v3, v209
	v_max_f32_e32 v238, 0.5, v238
	v_max_f32_e32 v239, 0.5, v239
	v_max_f32_e32 v154, 0.5, v154
	v_max_f32_e32 v155, 0.5, v155
	v_max_f32_e32 v156, 0.5, v156
	v_max_f32_e32 v157, 0.5, v157
	v_max_f32_e32 v2, 0.5, v2
	v_max_f32_e32 v3, 0.5, v3
	v_pk_mul_f32 v[246:247], v[238:239], v[246:247]
	v_pk_mul_f32 v[248:249], v[154:155], v[248:249]
	v_pk_mul_f32 v[250:251], v[156:157], v[250:251]
	v_pk_mul_f32 v[252:253], v[2:3], v[252:253]
	v_pk_mul_f32 v[64:65], v[64:65], v[246:247]
	v_pk_mul_f32 v[66:67], v[66:67], v[248:249]
	v_pk_mul_f32 v[60:61], v[60:61], v[250:251]
	v_pk_mul_f32 v[62:63], v[62:63], v[252:253]
	s_waitcnt vmcnt(12)
; __device__ __forceinline__ float fast_rcp(float x) { return __builtin_amdgcn_rcpf(x); }
;     __device__ __forceinline__ void operator()(f32x4 (&acc)[2][2][4][2], const Unit& u, int wr, int wc, int fr, int fq) const {
;     ...
;                 const int row = row0 + ai * HALF + m * 16;
; #pragma unroll
;                 for (int bj = 0; bj < 2; ++bj) {
;                     const int col = col0 + bj * 32;
;                     const unsigned char* grow = (const unsigned char*)Gt + (size_t)row * 4096 + col;
;                     const u32x2 gw = *(const u32x2*)(grow + 2048);
;                     f32x4 g0 = gate_d4(gw.x), g1 = gate_d4(gw.y);
;                     if (u.kind == 0) {
;                         const u32x2 aw = *(const u32x2*)grow;
;                         const f32x4 a0 = gate_d4(aw.x), a1 = gate_d4(aw.y);
; #pragma unroll
;                         for (int j = 0; j < 4; ++j) { g0[j] = a0[j] * fast_rcp(g0[j]); g1[j] = a1[j] * fast_rcp(g1[j]); }
;                         acc[ai][bj][m][0] *= g0; acc[ai][bj][m][1] *= g1;
	v_cvt_f32_ubyte0_e32 v246, v210
	v_cvt_f32_ubyte1_e32 v247, v210
	v_cvt_f32_ubyte2_e32 v248, v210
	v_cvt_f32_ubyte3_e32 v249, v210
	v_cvt_f32_ubyte0_e32 v250, v211
	v_cvt_f32_ubyte1_e32 v251, v211
	v_cvt_f32_ubyte2_e32 v252, v211
	v_cvt_f32_ubyte3_e32 v253, v211
	v_max_f32_e32 v246, 0.5, v246
	v_max_f32_e32 v247, 0.5, v247
	v_max_f32_e32 v248, 0.5, v248
	v_max_f32_e32 v249, 0.5, v249
	v_max_f32_e32 v250, 0.5, v250
	v_max_f32_e32 v251, 0.5, v251
	v_max_f32_e32 v252, 0.5, v252
	v_max_f32_e32 v253, 0.5, v253
	v_rcp_f32_e32 v246, v246
	v_rcp_f32_e32 v247, v247
	v_rcp_f32_e32 v248, v248
	v_rcp_f32_e32 v249, v249
	v_rcp_f32_e32 v250, v250
	v_rcp_f32_e32 v251, v251
	v_rcp_f32_e32 v252, v252
	v_rcp_f32_e32 v253, v253
	v_cvt_f32_ubyte0_e32 v238, v212
	v_cvt_f32_ubyte1_e32 v239, v212
	v_cvt_f32_ubyte2_e32 v154, v212
	v_cvt_f32_ubyte3_e32 v155, v212
	v_cvt_f32_ubyte0_e32 v156, v213
	v_cvt_f32_ubyte1_e32 v157, v213
	v_cvt_f32_ubyte2_e32 v2, v213
	v_cvt_f32_ubyte3_e32 v3, v213
	v_max_f32_e32 v238, 0.5, v238
	v_max_f32_e32 v239, 0.5, v239
	v_max_f32_e32 v154, 0.5, v154
	v_max_f32_e32 v155, 0.5, v155
	v_max_f32_e32 v156, 0.5, v156
	v_max_f32_e32 v157, 0.5, v157
	v_max_f32_e32 v2, 0.5, v2
	v_max_f32_e32 v3, 0.5, v3
	v_pk_mul_f32 v[246:247], v[238:239], v[246:247]
	v_pk_mul_f32 v[248:249], v[154:155], v[248:249]
	v_pk_mul_f32 v[250:251], v[156:157], v[250:251]
	v_pk_mul_f32 v[252:253], v[2:3], v[252:253]
	v_pk_mul_f32 v[32:33], v[32:33], v[246:247]
	v_pk_mul_f32 v[34:35], v[34:35], v[248:249]
	v_pk_mul_f32 v[28:29], v[28:29], v[250:251]
	v_pk_mul_f32 v[30:31], v[30:31], v[252:253]
	s_waitcnt vmcnt(10)
	v_cvt_f32_ubyte0_e32 v246, v214
	v_cvt_f32_ubyte1_e32 v247, v214
	v_cvt_f32_ubyte2_e32 v248, v214
	v_cvt_f32_ubyte3_e32 v249, v214
	v_cvt_f32_ubyte0_e32 v250, v215
	v_cvt_f32_ubyte1_e32 v251, v215
	v_cvt_f32_ubyte2_e32 v252, v215
	v_cvt_f32_ubyte3_e32 v253, v215
	v_max_f32_e32 v246, 0.5, v246
	v_max_f32_e32 v247, 0.5, v247
	v_max_f32_e32 v248, 0.5, v248
	v_max_f32_e32 v249, 0.5, v249
	v_max_f32_e32 v250, 0.5, v250
	v_max_f32_e32 v251, 0.5, v251
	v_max_f32_e32 v252, 0.5, v252
	v_max_f32_e32 v253, 0.5, v253
	v_rcp_f32_e32 v246, v246
	v_rcp_f32_e32 v247, v247
	v_rcp_f32_e32 v248, v248
	v_rcp_f32_e32 v249, v249
	v_rcp_f32_e32 v250, v250
	v_rcp_f32_e32 v251, v251
	v_rcp_f32_e32 v252, v252
	v_rcp_f32_e32 v253, v253
	v_cvt_f32_ubyte0_e32 v238, v216
	v_cvt_f32_ubyte1_e32 v239, v216
	v_cvt_f32_ubyte2_e32 v154, v216
	v_cvt_f32_ubyte3_e32 v155, v216
	v_cvt_f32_ubyte0_e32 v156, v217
	v_cvt_f32_ubyte1_e32 v157, v217
	v_cvt_f32_ubyte2_e32 v2, v217
	v_cvt_f32_ubyte3_e32 v3, v217
	v_max_f32_e32 v238, 0.5, v238
	v_max_f32_e32 v239, 0.5, v239
	v_max_f32_e32 v154, 0.5, v154
	v_max_f32_e32 v155, 0.5, v155
	v_max_f32_e32 v156, 0.5, v156
	v_max_f32_e32 v157, 0.5, v157
	v_max_f32_e32 v2, 0.5, v2
	v_max_f32_e32 v3, 0.5, v3
	v_pk_mul_f32 v[246:247], v[238:239], v[246:247]
	v_pk_mul_f32 v[248:249], v[154:155], v[248:249]
	v_pk_mul_f32 v[250:251], v[156:157], v[250:251]
	v_pk_mul_f32 v[252:253], v[2:3], v[252:253]
	v_pk_mul_f32 v[56:57], v[56:57], v[246:247]
	v_pk_mul_f32 v[58:59], v[58:59], v[248:249]
	v_pk_mul_f32 v[52:53], v[52:53], v[250:251]
	v_pk_mul_f32 v[54:55], v[54:55], v[252:253]
	s_waitcnt vmcnt(8)
	v_cvt_f32_ubyte0_e32 v246, v218
	v_cvt_f32_ubyte1_e32 v247, v218
	v_cvt_f32_ubyte2_e32 v248, v218
	v_cvt_f32_ubyte3_e32 v249, v218
	v_cvt_f32_ubyte0_e32 v250, v219
	v_cvt_f32_ubyte1_e32 v251, v219
	v_cvt_f32_ubyte2_e32 v252, v219
	v_cvt_f32_ubyte3_e32 v253, v219
	v_max_f32_e32 v246, 0.5, v246
	v_max_f32_e32 v247, 0.5, v247
	v_max_f32_e32 v248, 0.5, v248
	v_max_f32_e32 v249, 0.5, v249
	v_max_f32_e32 v250, 0.5, v250
	v_max_f32_e32 v251, 0.5, v251
	v_max_f32_e32 v252, 0.5, v252
	v_max_f32_e32 v253, 0.5, v253
	v_rcp_f32_e32 v246, v246
	v_rcp_f32_e32 v247, v247
	v_rcp_f32_e32 v248, v248
	v_rcp_f32_e32 v249, v249
	v_rcp_f32_e32 v250, v250
	v_rcp_f32_e32 v251, v251
	v_rcp_f32_e32 v252, v252
	v_rcp_f32_e32 v253, v253
	v_cvt_f32_ubyte0_e32 v238, v220
	v_cvt_f32_ubyte1_e32 v239, v220
	v_cvt_f32_ubyte2_e32 v154, v220
	v_cvt_f32_ubyte3_e32 v155, v220
	v_cvt_f32_ubyte0_e32 v156, v221
	v_cvt_f32_ubyte1_e32 v157, v221
	v_cvt_f32_ubyte2_e32 v2, v221
	v_cvt_f32_ubyte3_e32 v3, v221
	v_max_f32_e32 v238, 0.5, v238
	v_max_f32_e32 v239, 0.5, v239
	v_max_f32_e32 v154, 0.5, v154
	v_max_f32_e32 v155, 0.5, v155
	v_max_f32_e32 v156, 0.5, v156
	v_max_f32_e32 v157, 0.5, v157
	v_max_f32_e32 v2, 0.5, v2
	v_max_f32_e32 v3, 0.5, v3
	v_pk_mul_f32 v[246:247], v[238:239], v[246:247]
	v_pk_mul_f32 v[248:249], v[154:155], v[248:249]
	v_pk_mul_f32 v[250:251], v[156:157], v[250:251]
	v_pk_mul_f32 v[252:253], v[2:3], v[252:253]
	v_pk_mul_f32 v[24:25], v[24:25], v[246:247]
	v_pk_mul_f32 v[26:27], v[26:27], v[248:249]
	v_pk_mul_f32 v[20:21], v[20:21], v[250:251]
	v_pk_mul_f32 v[22:23], v[22:23], v[252:253]
	s_waitcnt vmcnt(6)
; __device__ __forceinline__ float fast_rcp(float x) { return __builtin_amdgcn_rcpf(x); }
;     __device__ __forceinline__ void operator()(f32x4 (&acc)[2][2][4][2], const Unit& u, int wr, int wc, int fr, int fq) const {
;     ...
;                 for (int bj = 0; bj < 2; ++bj) {
;                     const int col = col0 + bj * 32;
;                     const unsigned char* grow = (const unsigned char*)Gt + (size_t)row * 4096 + col;
;                     const u32x2 gw = *(const u32x2*)(grow + 2048);
;                     f32x4 g0 = gate_d4(gw.x), g1 = gate_d4(gw.y);
;                     if (u.kind == 0) {
;                         const u32x2 aw = *(const u32x2*)grow;
;                         const f32x4 a0 = gate_d4(aw.x), a1 = gate_d4(aw.y);
; #pragma unroll
;                         for (int j = 0; j < 4; ++j) { g0[j] = a0[j] * fast_rcp(g0[j]); g1[j] = a1[j] * fast_rcp(g1[j]); }
;                         acc[ai][bj][m][0] *= g0; acc[ai][bj][m][1] *= g1;
	v_cvt_f32_ubyte0_e32 v246, v222
	v_cvt_f32_ubyte1_e32 v247, v222
	v_cvt_f32_ubyte2_e32 v248, v222
	v_cvt_f32_ubyte3_e32 v249, v222
	v_cvt_f32_ubyte0_e32 v250, v223
	v_cvt_f32_ubyte1_e32 v251, v223
	v_cvt_f32_ubyte2_e32 v252, v223
	v_cvt_f32_ubyte3_e32 v253, v223
	v_max_f32_e32 v246, 0.5, v246
	v_max_f32_e32 v247, 0.5, v247
	v_max_f32_e32 v248, 0.5, v248
	v_max_f32_e32 v249, 0.5, v249
	v_max_f32_e32 v250, 0.5, v250
	v_max_f32_e32 v251, 0.5, v251
	v_max_f32_e32 v252, 0.5, v252
	v_max_f32_e32 v253, 0.5, v253
	v_rcp_f32_e32 v246, v246
	v_rcp_f32_e32 v247, v247
	v_rcp_f32_e32 v248, v248
	v_rcp_f32_e32 v249, v249
	v_rcp_f32_e32 v250, v250
	v_rcp_f32_e32 v251, v251
	v_rcp_f32_e32 v252, v252
	v_rcp_f32_e32 v253, v253
	v_cvt_f32_ubyte0_e32 v238, v224
	v_cvt_f32_ubyte1_e32 v239, v224
	v_cvt_f32_ubyte2_e32 v154, v224
	v_cvt_f32_ubyte3_e32 v155, v224
	v_cvt_f32_ubyte0_e32 v156, v225
	v_cvt_f32_ubyte1_e32 v157, v225
	v_cvt_f32_ubyte2_e32 v2, v225
	v_cvt_f32_ubyte3_e32 v3, v225
	v_max_f32_e32 v238, 0.5, v238
	v_max_f32_e32 v239, 0.5, v239
	v_max_f32_e32 v154, 0.5, v154
	v_max_f32_e32 v155, 0.5, v155
	v_max_f32_e32 v156, 0.5, v156
	v_max_f32_e32 v157, 0.5, v157
	v_max_f32_e32 v2, 0.5, v2
	v_max_f32_e32 v3, 0.5, v3
	v_pk_mul_f32 v[246:247], v[238:239], v[246:247]
	v_pk_mul_f32 v[248:249], v[154:155], v[248:249]
	v_pk_mul_f32 v[250:251], v[156:157], v[250:251]
	v_pk_mul_f32 v[252:253], v[2:3], v[252:253]
	v_pk_mul_f32 v[48:49], v[48:49], v[246:247]
	v_pk_mul_f32 v[50:51], v[50:51], v[248:249]
	v_pk_mul_f32 v[44:45], v[44:45], v[250:251]
	v_pk_mul_f32 v[46:47], v[46:47], v[252:253]
	s_waitcnt vmcnt(4)
	v_cvt_f32_ubyte0_e32 v246, v226
	v_cvt_f32_ubyte1_e32 v247, v226
	v_cvt_f32_ubyte2_e32 v248, v226
	v_cvt_f32_ubyte3_e32 v249, v226
	v_cvt_f32_ubyte0_e32 v250, v227
	v_cvt_f32_ubyte1_e32 v251, v227
	v_cvt_f32_ubyte2_e32 v252, v227
	v_cvt_f32_ubyte3_e32 v253, v227
	v_max_f32_e32 v246, 0.5, v246
	v_max_f32_e32 v247, 0.5, v247
	v_max_f32_e32 v248, 0.5, v248
	v_max_f32_e32 v249, 0.5, v249
	v_max_f32_e32 v250, 0.5, v250
	v_max_f32_e32 v251, 0.5, v251
	v_max_f32_e32 v252, 0.5, v252
	v_max_f32_e32 v253, 0.5, v253
	v_rcp_f32_e32 v246, v246
	v_rcp_f32_e32 v247, v247
	v_rcp_f32_e32 v248, v248
	v_rcp_f32_e32 v249, v249
	v_rcp_f32_e32 v250, v250
	v_rcp_f32_e32 v251, v251
	v_rcp_f32_e32 v252, v252
	v_rcp_f32_e32 v253, v253
	v_cvt_f32_ubyte0_e32 v238, v228
	v_cvt_f32_ubyte1_e32 v239, v228
	v_cvt_f32_ubyte2_e32 v154, v228
	v_cvt_f32_ubyte3_e32 v155, v228
	v_cvt_f32_ubyte0_e32 v156, v229
	v_cvt_f32_ubyte1_e32 v157, v229
	v_cvt_f32_ubyte2_e32 v2, v229
	v_cvt_f32_ubyte3_e32 v3, v229
	v_max_f32_e32 v238, 0.5, v238
	v_max_f32_e32 v239, 0.5, v239
	v_max_f32_e32 v154, 0.5, v154
	v_max_f32_e32 v155, 0.5, v155
	v_max_f32_e32 v156, 0.5, v156
	v_max_f32_e32 v157, 0.5, v157
	v_max_f32_e32 v2, 0.5, v2
	v_max_f32_e32 v3, 0.5, v3
	v_pk_mul_f32 v[246:247], v[238:239], v[246:247]
	v_pk_mul_f32 v[248:249], v[154:155], v[248:249]
	v_pk_mul_f32 v[250:251], v[156:157], v[250:251]
	v_pk_mul_f32 v[252:253], v[2:3], v[252:253]
	v_pk_mul_f32 v[16:17], v[16:17], v[246:247]
	v_pk_mul_f32 v[18:19], v[18:19], v[248:249]
	v_pk_mul_f32 v[12:13], v[12:13], v[250:251]
	v_pk_mul_f32 v[14:15], v[14:15], v[252:253]
	s_waitcnt vmcnt(2)
	v_cvt_f32_ubyte0_e32 v246, v230
	v_cvt_f32_ubyte1_e32 v247, v230
	v_cvt_f32_ubyte2_e32 v248, v230
	v_cvt_f32_ubyte3_e32 v249, v230
	v_cvt_f32_ubyte0_e32 v250, v231
	v_cvt_f32_ubyte1_e32 v251, v231
	v_cvt_f32_ubyte2_e32 v252, v231
	v_cvt_f32_ubyte3_e32 v253, v231
	v_max_f32_e32 v246, 0.5, v246
	v_max_f32_e32 v247, 0.5, v247
	v_max_f32_e32 v248, 0.5, v248
	v_max_f32_e32 v249, 0.5, v249
	v_max_f32_e32 v250, 0.5, v250
	v_max_f32_e32 v251, 0.5, v251
	v_max_f32_e32 v252, 0.5, v252
	v_max_f32_e32 v253, 0.5, v253
	v_rcp_f32_e32 v246, v246
	v_rcp_f32_e32 v247, v247
	v_rcp_f32_e32 v248, v248
	v_rcp_f32_e32 v249, v249
	v_rcp_f32_e32 v250, v250
	v_rcp_f32_e32 v251, v251
	v_rcp_f32_e32 v252, v252
	v_rcp_f32_e32 v253, v253
	v_cvt_f32_ubyte0_e32 v238, v232
	v_cvt_f32_ubyte1_e32 v239, v232
	v_cvt_f32_ubyte2_e32 v154, v232
	v_cvt_f32_ubyte3_e32 v155, v232
	v_cvt_f32_ubyte0_e32 v156, v233
	v_cvt_f32_ubyte1_e32 v157, v233
	v_cvt_f32_ubyte2_e32 v2, v233
	v_cvt_f32_ubyte3_e32 v3, v233
	v_max_f32_e32 v238, 0.5, v238
	v_max_f32_e32 v239, 0.5, v239
	v_max_f32_e32 v154, 0.5, v154
	v_max_f32_e32 v155, 0.5, v155
	v_max_f32_e32 v156, 0.5, v156
	v_max_f32_e32 v157, 0.5, v157
	v_max_f32_e32 v2, 0.5, v2
	v_max_f32_e32 v3, 0.5, v3
	v_pk_mul_f32 v[246:247], v[238:239], v[246:247]
	v_pk_mul_f32 v[248:249], v[154:155], v[248:249]
	v_pk_mul_f32 v[250:251], v[156:157], v[250:251]
	v_pk_mul_f32 v[252:253], v[2:3], v[252:253]
	v_pk_mul_f32 v[40:41], v[40:41], v[246:247]
	v_pk_mul_f32 v[42:43], v[42:43], v[248:249]
	v_pk_mul_f32 v[36:37], v[36:37], v[250:251]
	v_pk_mul_f32 v[38:39], v[38:39], v[252:253]
	s_waitcnt vmcnt(0)
	v_cvt_f32_ubyte0_e32 v246, v234
	v_cvt_f32_ubyte1_e32 v247, v234
	v_cvt_f32_ubyte2_e32 v248, v234
	v_cvt_f32_ubyte3_e32 v249, v234
	v_cvt_f32_ubyte0_e32 v250, v235
	v_cvt_f32_ubyte1_e32 v251, v235
	v_cvt_f32_ubyte2_e32 v252, v235
	v_cvt_f32_ubyte3_e32 v253, v235
	v_max_f32_e32 v246, 0.5, v246
	v_max_f32_e32 v247, 0.5, v247
	v_max_f32_e32 v248, 0.5, v248
	v_max_f32_e32 v249, 0.5, v249
	v_max_f32_e32 v250, 0.5, v250
	v_max_f32_e32 v251, 0.5, v251
	v_max_f32_e32 v252, 0.5, v252
	v_max_f32_e32 v253, 0.5, v253
	v_rcp_f32_e32 v246, v246
	v_rcp_f32_e32 v247, v247
	v_rcp_f32_e32 v248, v248
	v_rcp_f32_e32 v249, v249
	v_rcp_f32_e32 v250, v250
	v_rcp_f32_e32 v251, v251
	v_rcp_f32_e32 v252, v252
	v_rcp_f32_e32 v253, v253
	v_cvt_f32_ubyte0_e32 v238, v236
	v_cvt_f32_ubyte1_e32 v239, v236
	v_cvt_f32_ubyte2_e32 v154, v236
	v_cvt_f32_ubyte3_e32 v155, v236
	v_cvt_f32_ubyte0_e32 v156, v237
	v_cvt_f32_ubyte1_e32 v157, v237
	v_cvt_f32_ubyte2_e32 v2, v237
	v_cvt_f32_ubyte3_e32 v3, v237
	v_max_f32_e32 v238, 0.5, v238
	v_max_f32_e32 v239, 0.5, v239
	v_max_f32_e32 v154, 0.5, v154
	v_max_f32_e32 v155, 0.5, v155
	v_max_f32_e32 v156, 0.5, v156
	v_max_f32_e32 v157, 0.5, v157
	v_max_f32_e32 v2, 0.5, v2
	v_max_f32_e32 v3, 0.5, v3
	v_pk_mul_f32 v[246:247], v[238:239], v[246:247]
	v_pk_mul_f32 v[248:249], v[154:155], v[248:249]
	v_pk_mul_f32 v[250:251], v[156:157], v[250:251]
	v_pk_mul_f32 v[252:253], v[2:3], v[252:253]
	v_pk_mul_f32 v[8:9], v[8:9], v[246:247]
	v_pk_mul_f32 v[10:11], v[10:11], v[248:249]
	v_pk_mul_f32 v[4:5], v[4:5], v[250:251]
	v_pk_mul_f32 v[6:7], v[6:7], v[252:253]
	s_mov_b64 s[40:41], -1
	s_branch .Lp3e_done
; __device__ __forceinline__ float fast_rcp(float x) { return __builtin_amdgcn_rcpf(x); }
; __device__ __forceinline__ u32x4 pack8(f32x4 a, f32x4 b) { u32x4 w; w.x = cvt_pk_bf16(a[0], a[1]); w.y = cvt_pk_bf16(a[2], a[3]); w.z = cvt_pk_bf16(b[0], b[1]); w.w = cvt_pk_bf16(b[2], b[3]); return w; }
;     __device__ __forceinline__ void operator()(f32x4 (&acc)[2][2][4][2], const Unit& u, int wr, int wc, int fr, int fq) const {
;     ...
;                 for (int bj = 0; bj < 2; ++bj) {
;                     const int col = col0 + bj * 32;
;                     const unsigned char* grow = (const unsigned char*)Gt + (size_t)row * 4096 + col;
;                     const u32x2 gw = *(const u32x2*)(grow + 2048);
;                     f32x4 g0 = gate_d4(gw.x), g1 = gate_d4(gw.y);
;                     if (u.kind == 0) {
;                         const u32x2 aw = *(const u32x2*)grow;
;                         const f32x4 a0 = gate_d4(aw.x), a1 = gate_d4(aw.y);
; #pragma unroll
;                         for (int j = 0; j < 4; ++j) { g0[j] = a0[j] * fast_rcp(g0[j]); g1[j] = a1[j] * fast_rcp(g1[j]); }
;                         acc[ai][bj][m][0] *= g0; acc[ai][bj][m][1] *= g1;
;                     } else {
;                         *(u32x4*)(MG + (size_t)row * D + col) = pack8(acc[ai][bj][m][0] * (g0 * (1.0f / 255.0f)), acc[ai][bj][m][1] * (g1 * (1.0f / 255.0f)));
;                     }
.Lp3e_k1:
	v_add_u32_e32 v144, v146, v145
	s_waitcnt vmcnt(15)
	v_cvt_f32_ubyte0_e32 v246, v174
	v_cvt_f32_ubyte1_e32 v247, v174
	v_cvt_f32_ubyte2_e32 v248, v174
	v_cvt_f32_ubyte3_e32 v249, v174
	v_cvt_f32_ubyte0_e32 v250, v175
	v_cvt_f32_ubyte1_e32 v251, v175
	v_cvt_f32_ubyte2_e32 v252, v175
	v_cvt_f32_ubyte3_e32 v253, v175
	v_max_f32_e32 v246, 0.5, v246
	v_max_f32_e32 v247, 0.5, v247
	v_max_f32_e32 v248, 0.5, v248
	v_max_f32_e32 v249, 0.5, v249
	v_max_f32_e32 v250, 0.5, v250
	v_max_f32_e32 v251, 0.5, v251
	v_max_f32_e32 v252, 0.5, v252
	v_max_f32_e32 v253, 0.5, v253
	v_pk_mul_f32 v[246:247], v[246:247], s[28:29] op_sel_hi:[1,0]
	v_pk_mul_f32 v[248:249], v[248:249], s[28:29] op_sel_hi:[1,0]
	v_pk_mul_f32 v[250:251], v[250:251], s[28:29] op_sel_hi:[1,0]
	v_pk_mul_f32 v[252:253], v[252:253], s[28:29] op_sel_hi:[1,0]
	v_pk_mul_f32 v[128:129], v[128:129], v[246:247]
	v_pk_mul_f32 v[130:131], v[130:131], v[248:249]
	v_pk_mul_f32 v[124:125], v[124:125], v[250:251]
	v_pk_mul_f32 v[126:127], v[126:127], v[252:253]
	v_cvt_pk_bf16_f32 v206, v128, v129
	v_cvt_pk_bf16_f32 v207, v130, v131
	v_cvt_pk_bf16_f32 v208, v124, v125
	v_cvt_pk_bf16_f32 v209, v126, v127
	global_store_dwordx4 v144, v[206:209], s[42:43]
	s_waitcnt vmcnt(15)
	v_cvt_f32_ubyte0_e32 v246, v176
	v_cvt_f32_ubyte1_e32 v247, v176
	v_cvt_f32_ubyte2_e32 v248, v176
	v_cvt_f32_ubyte3_e32 v249, v176
	v_cvt_f32_ubyte0_e32 v250, v177
	v_cvt_f32_ubyte1_e32 v251, v177
	v_cvt_f32_ubyte2_e32 v252, v177
	v_cvt_f32_ubyte3_e32 v253, v177
	v_max_f32_e32 v246, 0.5, v246
	v_max_f32_e32 v247, 0.5, v247
	v_max_f32_e32 v248, 0.5, v248
	v_max_f32_e32 v249, 0.5, v249
	v_max_f32_e32 v250, 0.5, v250
	v_max_f32_e32 v251, 0.5, v251
	v_max_f32_e32 v252, 0.5, v252
	v_max_f32_e32 v253, 0.5, v253
	v_pk_mul_f32 v[246:247], v[246:247], s[28:29] op_sel_hi:[1,0]
	v_pk_mul_f32 v[248:249], v[248:249], s[28:29] op_sel_hi:[1,0]
	v_pk_mul_f32 v[250:251], v[250:251], s[28:29] op_sel_hi:[1,0]
	v_pk_mul_f32 v[252:253], v[252:253], s[28:29] op_sel_hi:[1,0]
	v_pk_mul_f32 v[96:97], v[96:97], v[246:247]
	v_pk_mul_f32 v[98:99], v[98:99], v[248:249]
	v_pk_mul_f32 v[92:93], v[92:93], v[250:251]
	v_pk_mul_f32 v[94:95], v[94:95], v[252:253]
	v_cvt_pk_bf16_f32 v210, v96, v97
	v_cvt_pk_bf16_f32 v211, v98, v99
	v_cvt_pk_bf16_f32 v212, v92, v93
	v_cvt_pk_bf16_f32 v213, v94, v95
	global_store_dwordx4 v144, v[210:213], s[42:43] offset:64
	v_add_u32_e32 v0, v147, v145
	s_waitcnt vmcnt(15)
	v_cvt_f32_ubyte0_e32 v246, v178
	v_cvt_f32_ubyte1_e32 v247, v178
	v_cvt_f32_ubyte2_e32 v248, v178
	v_cvt_f32_ubyte3_e32 v249, v178
	v_cvt_f32_ubyte0_e32 v250, v179
	v_cvt_f32_ubyte1_e32 v251, v179
	v_cvt_f32_ubyte2_e32 v252, v179
	v_cvt_f32_ubyte3_e32 v253, v179
	v_max_f32_e32 v246, 0.5, v246
	v_max_f32_e32 v247, 0.5, v247
	v_max_f32_e32 v248, 0.5, v248
	v_max_f32_e32 v249, 0.5, v249
	v_max_f32_e32 v250, 0.5, v250
	v_max_f32_e32 v251, 0.5, v251
	v_max_f32_e32 v252, 0.5, v252
	v_max_f32_e32 v253, 0.5, v253
	v_pk_mul_f32 v[246:247], v[246:247], s[28:29] op_sel_hi:[1,0]
	v_pk_mul_f32 v[248:249], v[248:249], s[28:29] op_sel_hi:[1,0]
	v_pk_mul_f32 v[250:251], v[250:251], s[28:29] op_sel_hi:[1,0]
	v_pk_mul_f32 v[252:253], v[252:253], s[28:29] op_sel_hi:[1,0]
	v_pk_mul_f32 v[120:121], v[120:121], v[246:247]
	v_pk_mul_f32 v[122:123], v[122:123], v[248:249]
	v_pk_mul_f32 v[116:117], v[116:117], v[250:251]
	v_pk_mul_f32 v[118:119], v[118:119], v[252:253]
	v_cvt_pk_bf16_f32 v214, v120, v121
	v_cvt_pk_bf16_f32 v215, v122, v123
	v_cvt_pk_bf16_f32 v216, v116, v117
	v_cvt_pk_bf16_f32 v217, v118, v119
	global_store_dwordx4 v0, v[214:217], s[42:43]
	s_waitcnt vmcnt(15)
	v_cvt_f32_ubyte0_e32 v246, v180
	v_cvt_f32_ubyte1_e32 v247, v180
	v_cvt_f32_ubyte2_e32 v248, v180
	v_cvt_f32_ubyte3_e32 v249, v180
	v_cvt_f32_ubyte0_e32 v250, v181
	v_cvt_f32_ubyte1_e32 v251, v181
	v_cvt_f32_ubyte2_e32 v252, v181
	v_cvt_f32_ubyte3_e32 v253, v181
	v_max_f32_e32 v246, 0.5, v246
	v_max_f32_e32 v247, 0.5, v247
	v_max_f32_e32 v248, 0.5, v248
	v_max_f32_e32 v249, 0.5, v249
	v_max_f32_e32 v250, 0.5, v250
	v_max_f32_e32 v251, 0.5, v251
	v_max_f32_e32 v252, 0.5, v252
	v_max_f32_e32 v253, 0.5, v253
	v_pk_mul_f32 v[246:247], v[246:247], s[28:29] op_sel_hi:[1,0]
	v_pk_mul_f32 v[248:249], v[248:249], s[28:29] op_sel_hi:[1,0]
	v_pk_mul_f32 v[250:251], v[250:251], s[28:29] op_sel_hi:[1,0]
	v_pk_mul_f32 v[252:253], v[252:253], s[28:29] op_sel_hi:[1,0]
	v_pk_mul_f32 v[88:89], v[88:89], v[246:247]
	v_pk_mul_f32 v[90:91], v[90:91], v[248:249]
	v_pk_mul_f32 v[84:85], v[84:85], v[250:251]
	v_pk_mul_f32 v[86:87], v[86:87], v[252:253]
	v_cvt_pk_bf16_f32 v218, v88, v89
	v_cvt_pk_bf16_f32 v219, v90, v91
	v_cvt_pk_bf16_f32 v220, v84, v85
	v_cvt_pk_bf16_f32 v221, v86, v87
	global_store_dwordx4 v0, v[218:221], s[42:43] offset:64
	v_add_u32_e32 v144, v148, v145
	s_waitcnt vmcnt(15)
	v_cvt_f32_ubyte0_e32 v246, v182
	v_cvt_f32_ubyte1_e32 v247, v182
	v_cvt_f32_ubyte2_e32 v248, v182
	v_cvt_f32_ubyte3_e32 v249, v182
	v_cvt_f32_ubyte0_e32 v250, v183
	v_cvt_f32_ubyte1_e32 v251, v183
	v_cvt_f32_ubyte2_e32 v252, v183
	v_cvt_f32_ubyte3_e32 v253, v183
	v_max_f32_e32 v246, 0.5, v246
	v_max_f32_e32 v247, 0.5, v247
	v_max_f32_e32 v248, 0.5, v248
	v_max_f32_e32 v249, 0.5, v249
	v_max_f32_e32 v250, 0.5, v250
	v_max_f32_e32 v251, 0.5, v251
	v_max_f32_e32 v252, 0.5, v252
	v_max_f32_e32 v253, 0.5, v253
	v_pk_mul_f32 v[246:247], v[246:247], s[28:29] op_sel_hi:[1,0]
	v_pk_mul_f32 v[248:249], v[248:249], s[28:29] op_sel_hi:[1,0]
	v_pk_mul_f32 v[250:251], v[250:251], s[28:29] op_sel_hi:[1,0]
	v_pk_mul_f32 v[252:253], v[252:253], s[28:29] op_sel_hi:[1,0]
	v_pk_mul_f32 v[112:113], v[112:113], v[246:247]
	v_pk_mul_f32 v[114:115], v[114:115], v[248:249]
	v_pk_mul_f32 v[108:109], v[108:109], v[250:251]
	v_pk_mul_f32 v[110:111], v[110:111], v[252:253]
	v_cvt_pk_bf16_f32 v222, v112, v113
	v_cvt_pk_bf16_f32 v223, v114, v115
	v_cvt_pk_bf16_f32 v224, v108, v109
	v_cvt_pk_bf16_f32 v225, v110, v111
	global_store_dwordx4 v144, v[222:225], s[42:43]
	s_waitcnt vmcnt(15)
; __device__ __forceinline__ float fast_rcp(float x) { return __builtin_amdgcn_rcpf(x); }
; __device__ __forceinline__ u32x4 pack8(f32x4 a, f32x4 b) { u32x4 w; w.x = cvt_pk_bf16(a[0], a[1]); w.y = cvt_pk_bf16(a[2], a[3]); w.z = cvt_pk_bf16(b[0], b[1]); w.w = cvt_pk_bf16(b[2], b[3]); return w; }
;     __device__ __forceinline__ void operator()(f32x4 (&acc)[2][2][4][2], const Unit& u, int wr, int wc, int fr, int fq) const {
;     ...
;                 for (int bj = 0; bj < 2; ++bj) {
;                     const int col = col0 + bj * 32;
;                     const unsigned char* grow = (const unsigned char*)Gt + (size_t)row * 4096 + col;
;                     const u32x2 gw = *(const u32x2*)(grow + 2048);
;                     f32x4 g0 = gate_d4(gw.x), g1 = gate_d4(gw.y);
;                     if (u.kind == 0) {
;                         const u32x2 aw = *(const u32x2*)grow;
;                         const f32x4 a0 = gate_d4(aw.x), a1 = gate_d4(aw.y);
; #pragma unroll
;                         for (int j = 0; j < 4; ++j) { g0[j] = a0[j] * fast_rcp(g0[j]); g1[j] = a1[j] * fast_rcp(g1[j]); }
;                         acc[ai][bj][m][0] *= g0; acc[ai][bj][m][1] *= g1;
;                     } else {
;                         *(u32x4*)(MG + (size_t)row * D + col) = pack8(acc[ai][bj][m][0] * (g0 * (1.0f / 255.0f)), acc[ai][bj][m][1] * (g1 * (1.0f / 255.0f)));
;                     }
	v_cvt_f32_ubyte0_e32 v246, v184
	v_cvt_f32_ubyte1_e32 v247, v184
	v_cvt_f32_ubyte2_e32 v248, v184
	v_cvt_f32_ubyte3_e32 v249, v184
	v_cvt_f32_ubyte0_e32 v250, v185
	v_cvt_f32_ubyte1_e32 v251, v185
	v_cvt_f32_ubyte2_e32 v252, v185
	v_cvt_f32_ubyte3_e32 v253, v185
	v_max_f32_e32 v246, 0.5, v246
	v_max_f32_e32 v247, 0.5, v247
	v_max_f32_e32 v248, 0.5, v248
	v_max_f32_e32 v249, 0.5, v249
	v_max_f32_e32 v250, 0.5, v250
	v_max_f32_e32 v251, 0.5, v251
	v_max_f32_e32 v252, 0.5, v252
	v_max_f32_e32 v253, 0.5, v253
	v_pk_mul_f32 v[246:247], v[246:247], s[28:29] op_sel_hi:[1,0]
	v_pk_mul_f32 v[248:249], v[248:249], s[28:29] op_sel_hi:[1,0]
	v_pk_mul_f32 v[250:251], v[250:251], s[28:29] op_sel_hi:[1,0]
	v_pk_mul_f32 v[252:253], v[252:253], s[28:29] op_sel_hi:[1,0]
	v_pk_mul_f32 v[80:81], v[80:81], v[246:247]
	v_pk_mul_f32 v[82:83], v[82:83], v[248:249]
	v_pk_mul_f32 v[76:77], v[76:77], v[250:251]
	v_pk_mul_f32 v[78:79], v[78:79], v[252:253]
	v_cvt_pk_bf16_f32 v226, v80, v81
	v_cvt_pk_bf16_f32 v227, v82, v83
	v_cvt_pk_bf16_f32 v228, v76, v77
	v_cvt_pk_bf16_f32 v229, v78, v79
	global_store_dwordx4 v144, v[226:229], s[42:43] offset:64
	v_add_u32_e32 v0, v149, v145
	s_waitcnt vmcnt(15)
	v_cvt_f32_ubyte0_e32 v246, v186
	v_cvt_f32_ubyte1_e32 v247, v186
	v_cvt_f32_ubyte2_e32 v248, v186
	v_cvt_f32_ubyte3_e32 v249, v186
	v_cvt_f32_ubyte0_e32 v250, v187
	v_cvt_f32_ubyte1_e32 v251, v187
	v_cvt_f32_ubyte2_e32 v252, v187
	v_cvt_f32_ubyte3_e32 v253, v187
	v_max_f32_e32 v246, 0.5, v246
	v_max_f32_e32 v247, 0.5, v247
	v_max_f32_e32 v248, 0.5, v248
	v_max_f32_e32 v249, 0.5, v249
	v_max_f32_e32 v250, 0.5, v250
	v_max_f32_e32 v251, 0.5, v251
	v_max_f32_e32 v252, 0.5, v252
	v_max_f32_e32 v253, 0.5, v253
	v_pk_mul_f32 v[246:247], v[246:247], s[28:29] op_sel_hi:[1,0]
	v_pk_mul_f32 v[248:249], v[248:249], s[28:29] op_sel_hi:[1,0]
	v_pk_mul_f32 v[250:251], v[250:251], s[28:29] op_sel_hi:[1,0]
	v_pk_mul_f32 v[252:253], v[252:253], s[28:29] op_sel_hi:[1,0]
	v_pk_mul_f32 v[104:105], v[104:105], v[246:247]
	v_pk_mul_f32 v[106:107], v[106:107], v[248:249]
	v_pk_mul_f32 v[100:101], v[100:101], v[250:251]
	v_pk_mul_f32 v[102:103], v[102:103], v[252:253]
	v_cvt_pk_bf16_f32 v230, v104, v105
	v_cvt_pk_bf16_f32 v231, v106, v107
	v_cvt_pk_bf16_f32 v232, v100, v101
	v_cvt_pk_bf16_f32 v233, v102, v103
	global_store_dwordx4 v0, v[230:233], s[42:43]
	s_waitcnt vmcnt(15)
	v_cvt_f32_ubyte0_e32 v246, v188
	v_cvt_f32_ubyte1_e32 v247, v188
	v_cvt_f32_ubyte2_e32 v248, v188
	v_cvt_f32_ubyte3_e32 v249, v188
	v_cvt_f32_ubyte0_e32 v250, v189
	v_cvt_f32_ubyte1_e32 v251, v189
	v_cvt_f32_ubyte2_e32 v252, v189
	v_cvt_f32_ubyte3_e32 v253, v189
	v_max_f32_e32 v246, 0.5, v246
	v_max_f32_e32 v247, 0.5, v247
	v_max_f32_e32 v248, 0.5, v248
	v_max_f32_e32 v249, 0.5, v249
	v_max_f32_e32 v250, 0.5, v250
	v_max_f32_e32 v251, 0.5, v251
	v_max_f32_e32 v252, 0.5, v252
	v_max_f32_e32 v253, 0.5, v253
	v_pk_mul_f32 v[246:247], v[246:247], s[28:29] op_sel_hi:[1,0]
	v_pk_mul_f32 v[248:249], v[248:249], s[28:29] op_sel_hi:[1,0]
	v_pk_mul_f32 v[250:251], v[250:251], s[28:29] op_sel_hi:[1,0]
	v_pk_mul_f32 v[252:253], v[252:253], s[28:29] op_sel_hi:[1,0]
	v_pk_mul_f32 v[72:73], v[72:73], v[246:247]
	v_pk_mul_f32 v[74:75], v[74:75], v[248:249]
	v_pk_mul_f32 v[68:69], v[68:69], v[250:251]
	v_pk_mul_f32 v[70:71], v[70:71], v[252:253]
	v_cvt_pk_bf16_f32 v234, v72, v73
	v_cvt_pk_bf16_f32 v235, v74, v75
	v_cvt_pk_bf16_f32 v236, v68, v69
	v_cvt_pk_bf16_f32 v237, v70, v71
	global_store_dwordx4 v0, v[234:237], s[42:43] offset:64
	v_add_u32_e32 v144, v150, v145
	s_waitcnt vmcnt(15)
	v_cvt_f32_ubyte0_e32 v246, v190
	v_cvt_f32_ubyte1_e32 v247, v190
	v_cvt_f32_ubyte2_e32 v248, v190
	v_cvt_f32_ubyte3_e32 v249, v190
	v_cvt_f32_ubyte0_e32 v250, v191
	v_cvt_f32_ubyte1_e32 v251, v191
	v_cvt_f32_ubyte2_e32 v252, v191
	v_cvt_f32_ubyte3_e32 v253, v191
	v_max_f32_e32 v246, 0.5, v246
	v_max_f32_e32 v247, 0.5, v247
	v_max_f32_e32 v248, 0.5, v248
	v_max_f32_e32 v249, 0.5, v249
	v_max_f32_e32 v250, 0.5, v250
	v_max_f32_e32 v251, 0.5, v251
	v_max_f32_e32 v252, 0.5, v252
	v_max_f32_e32 v253, 0.5, v253
	v_pk_mul_f32 v[246:247], v[246:247], s[28:29] op_sel_hi:[1,0]
	v_pk_mul_f32 v[248:249], v[248:249], s[28:29] op_sel_hi:[1,0]
	v_pk_mul_f32 v[250:251], v[250:251], s[28:29] op_sel_hi:[1,0]
	v_pk_mul_f32 v[252:253], v[252:253], s[28:29] op_sel_hi:[1,0]
	v_pk_mul_f32 v[64:65], v[64:65], v[246:247]
	v_pk_mul_f32 v[66:67], v[66:67], v[248:249]
	v_pk_mul_f32 v[60:61], v[60:61], v[250:251]
	v_pk_mul_f32 v[62:63], v[62:63], v[252:253]
	v_cvt_pk_bf16_f32 v206, v64, v65
	v_cvt_pk_bf16_f32 v207, v66, v67
	v_cvt_pk_bf16_f32 v208, v60, v61
	v_cvt_pk_bf16_f32 v209, v62, v63
	global_store_dwordx4 v144, v[206:209], s[42:43]
	s_waitcnt vmcnt(15)
	v_cvt_f32_ubyte0_e32 v246, v192
	v_cvt_f32_ubyte1_e32 v247, v192
	v_cvt_f32_ubyte2_e32 v248, v192
	v_cvt_f32_ubyte3_e32 v249, v192
	v_cvt_f32_ubyte0_e32 v250, v193
	v_cvt_f32_ubyte1_e32 v251, v193
	v_cvt_f32_ubyte2_e32 v252, v193
	v_cvt_f32_ubyte3_e32 v253, v193
	v_max_f32_e32 v246, 0.5, v246
	v_max_f32_e32 v247, 0.5, v247
	v_max_f32_e32 v248, 0.5, v248
	v_max_f32_e32 v249, 0.5, v249
	v_max_f32_e32 v250, 0.5, v250
	v_max_f32_e32 v251, 0.5, v251
	v_max_f32_e32 v252, 0.5, v252
	v_max_f32_e32 v253, 0.5, v253
	v_pk_mul_f32 v[246:247], v[246:247], s[28:29] op_sel_hi:[1,0]
	v_pk_mul_f32 v[248:249], v[248:249], s[28:29] op_sel_hi:[1,0]
	v_pk_mul_f32 v[250:251], v[250:251], s[28:29] op_sel_hi:[1,0]
	v_pk_mul_f32 v[252:253], v[252:253], s[28:29] op_sel_hi:[1,0]
	v_pk_mul_f32 v[32:33], v[32:33], v[246:247]
	v_pk_mul_f32 v[34:35], v[34:35], v[248:249]
	v_pk_mul_f32 v[28:29], v[28:29], v[250:251]
	v_pk_mul_f32 v[30:31], v[30:31], v[252:253]
	v_cvt_pk_bf16_f32 v210, v32, v33
	v_cvt_pk_bf16_f32 v211, v34, v35
	v_cvt_pk_bf16_f32 v212, v28, v29
	v_cvt_pk_bf16_f32 v213, v30, v31
	global_store_dwordx4 v144, v[210:213], s[42:43] offset:64
	v_add_u32_e32 v0, v151, v145
	s_waitcnt vmcnt(15)
; __device__ __forceinline__ float fast_rcp(float x) { return __builtin_amdgcn_rcpf(x); }
; __device__ __forceinline__ u32x4 pack8(f32x4 a, f32x4 b) { u32x4 w; w.x = cvt_pk_bf16(a[0], a[1]); w.y = cvt_pk_bf16(a[2], a[3]); w.z = cvt_pk_bf16(b[0], b[1]); w.w = cvt_pk_bf16(b[2], b[3]); return w; }
;     __device__ __forceinline__ void operator()(f32x4 (&acc)[2][2][4][2], const Unit& u, int wr, int wc, int fr, int fq) const {
;     ...
;                 for (int bj = 0; bj < 2; ++bj) {
;                     const int col = col0 + bj * 32;
;                     const unsigned char* grow = (const unsigned char*)Gt + (size_t)row * 4096 + col;
;                     const u32x2 gw = *(const u32x2*)(grow + 2048);
;                     f32x4 g0 = gate_d4(gw.x), g1 = gate_d4(gw.y);
;                     if (u.kind == 0) {
;                         const u32x2 aw = *(const u32x2*)grow;
;                         const f32x4 a0 = gate_d4(aw.x), a1 = gate_d4(aw.y);
; #pragma unroll
;                         for (int j = 0; j < 4; ++j) { g0[j] = a0[j] * fast_rcp(g0[j]); g1[j] = a1[j] * fast_rcp(g1[j]); }
;                         acc[ai][bj][m][0] *= g0; acc[ai][bj][m][1] *= g1;
;                     } else {
;                         *(u32x4*)(MG + (size_t)row * D + col) = pack8(acc[ai][bj][m][0] * (g0 * (1.0f / 255.0f)), acc[ai][bj][m][1] * (g1 * (1.0f / 255.0f)));
;                     }
	v_cvt_f32_ubyte0_e32 v246, v194
	v_cvt_f32_ubyte1_e32 v247, v194
	v_cvt_f32_ubyte2_e32 v248, v194
	v_cvt_f32_ubyte3_e32 v249, v194
	v_cvt_f32_ubyte0_e32 v250, v195
	v_cvt_f32_ubyte1_e32 v251, v195
	v_cvt_f32_ubyte2_e32 v252, v195
	v_cvt_f32_ubyte3_e32 v253, v195
	v_max_f32_e32 v246, 0.5, v246
	v_max_f32_e32 v247, 0.5, v247
	v_max_f32_e32 v248, 0.5, v248
	v_max_f32_e32 v249, 0.5, v249
	v_max_f32_e32 v250, 0.5, v250
	v_max_f32_e32 v251, 0.5, v251
	v_max_f32_e32 v252, 0.5, v252
	v_max_f32_e32 v253, 0.5, v253
	v_pk_mul_f32 v[246:247], v[246:247], s[28:29] op_sel_hi:[1,0]
	v_pk_mul_f32 v[248:249], v[248:249], s[28:29] op_sel_hi:[1,0]
	v_pk_mul_f32 v[250:251], v[250:251], s[28:29] op_sel_hi:[1,0]
	v_pk_mul_f32 v[252:253], v[252:253], s[28:29] op_sel_hi:[1,0]
	v_pk_mul_f32 v[56:57], v[56:57], v[246:247]
	v_pk_mul_f32 v[58:59], v[58:59], v[248:249]
	v_pk_mul_f32 v[52:53], v[52:53], v[250:251]
	v_pk_mul_f32 v[54:55], v[54:55], v[252:253]
	v_cvt_pk_bf16_f32 v214, v56, v57
	v_cvt_pk_bf16_f32 v215, v58, v59
	v_cvt_pk_bf16_f32 v216, v52, v53
	v_cvt_pk_bf16_f32 v217, v54, v55
	global_store_dwordx4 v0, v[214:217], s[42:43]
	s_waitcnt vmcnt(15)
	v_cvt_f32_ubyte0_e32 v246, v196
	v_cvt_f32_ubyte1_e32 v247, v196
	v_cvt_f32_ubyte2_e32 v248, v196
	v_cvt_f32_ubyte3_e32 v249, v196
	v_cvt_f32_ubyte0_e32 v250, v197
	v_cvt_f32_ubyte1_e32 v251, v197
	v_cvt_f32_ubyte2_e32 v252, v197
	v_cvt_f32_ubyte3_e32 v253, v197
	v_max_f32_e32 v246, 0.5, v246
	v_max_f32_e32 v247, 0.5, v247
	v_max_f32_e32 v248, 0.5, v248
	v_max_f32_e32 v249, 0.5, v249
	v_max_f32_e32 v250, 0.5, v250
	v_max_f32_e32 v251, 0.5, v251
	v_max_f32_e32 v252, 0.5, v252
	v_max_f32_e32 v253, 0.5, v253
	v_pk_mul_f32 v[246:247], v[246:247], s[28:29] op_sel_hi:[1,0]
	v_pk_mul_f32 v[248:249], v[248:249], s[28:29] op_sel_hi:[1,0]
	v_pk_mul_f32 v[250:251], v[250:251], s[28:29] op_sel_hi:[1,0]
	v_pk_mul_f32 v[252:253], v[252:253], s[28:29] op_sel_hi:[1,0]
	v_pk_mul_f32 v[24:25], v[24:25], v[246:247]
	v_pk_mul_f32 v[26:27], v[26:27], v[248:249]
	v_pk_mul_f32 v[20:21], v[20:21], v[250:251]
	v_pk_mul_f32 v[22:23], v[22:23], v[252:253]
	v_cvt_pk_bf16_f32 v218, v24, v25
	v_cvt_pk_bf16_f32 v219, v26, v27
	v_cvt_pk_bf16_f32 v220, v20, v21
	v_cvt_pk_bf16_f32 v221, v22, v23
	global_store_dwordx4 v0, v[218:221], s[42:43] offset:64
	v_add_u32_e32 v144, v152, v145
	s_waitcnt vmcnt(15)
	v_cvt_f32_ubyte0_e32 v246, v198
	v_cvt_f32_ubyte1_e32 v247, v198
	v_cvt_f32_ubyte2_e32 v248, v198
	v_cvt_f32_ubyte3_e32 v249, v198
	v_cvt_f32_ubyte0_e32 v250, v199
	v_cvt_f32_ubyte1_e32 v251, v199
	v_cvt_f32_ubyte2_e32 v252, v199
	v_cvt_f32_ubyte3_e32 v253, v199
	v_max_f32_e32 v246, 0.5, v246
	v_max_f32_e32 v247, 0.5, v247
	v_max_f32_e32 v248, 0.5, v248
	v_max_f32_e32 v249, 0.5, v249
	v_max_f32_e32 v250, 0.5, v250
	v_max_f32_e32 v251, 0.5, v251
	v_max_f32_e32 v252, 0.5, v252
	v_max_f32_e32 v253, 0.5, v253
	v_pk_mul_f32 v[246:247], v[246:247], s[28:29] op_sel_hi:[1,0]
	v_pk_mul_f32 v[248:249], v[248:249], s[28:29] op_sel_hi:[1,0]
	v_pk_mul_f32 v[250:251], v[250:251], s[28:29] op_sel_hi:[1,0]
	v_pk_mul_f32 v[252:253], v[252:253], s[28:29] op_sel_hi:[1,0]
	v_pk_mul_f32 v[48:49], v[48:49], v[246:247]
	v_pk_mul_f32 v[50:51], v[50:51], v[248:249]
	v_pk_mul_f32 v[44:45], v[44:45], v[250:251]
	v_pk_mul_f32 v[46:47], v[46:47], v[252:253]
	v_cvt_pk_bf16_f32 v222, v48, v49
	v_cvt_pk_bf16_f32 v223, v50, v51
	v_cvt_pk_bf16_f32 v224, v44, v45
	v_cvt_pk_bf16_f32 v225, v46, v47
	global_store_dwordx4 v144, v[222:225], s[42:43]
	s_waitcnt vmcnt(15)
	v_cvt_f32_ubyte0_e32 v246, v200
	v_cvt_f32_ubyte1_e32 v247, v200
	v_cvt_f32_ubyte2_e32 v248, v200
	v_cvt_f32_ubyte3_e32 v249, v200
	v_cvt_f32_ubyte0_e32 v250, v201
	v_cvt_f32_ubyte1_e32 v251, v201
	v_cvt_f32_ubyte2_e32 v252, v201
	v_cvt_f32_ubyte3_e32 v253, v201
	v_max_f32_e32 v246, 0.5, v246
	v_max_f32_e32 v247, 0.5, v247
	v_max_f32_e32 v248, 0.5, v248
	v_max_f32_e32 v249, 0.5, v249
	v_max_f32_e32 v250, 0.5, v250
	v_max_f32_e32 v251, 0.5, v251
	v_max_f32_e32 v252, 0.5, v252
	v_max_f32_e32 v253, 0.5, v253
	v_pk_mul_f32 v[246:247], v[246:247], s[28:29] op_sel_hi:[1,0]
	v_pk_mul_f32 v[248:249], v[248:249], s[28:29] op_sel_hi:[1,0]
	v_pk_mul_f32 v[250:251], v[250:251], s[28:29] op_sel_hi:[1,0]
	v_pk_mul_f32 v[252:253], v[252:253], s[28:29] op_sel_hi:[1,0]
	v_pk_mul_f32 v[16:17], v[16:17], v[246:247]
	v_pk_mul_f32 v[18:19], v[18:19], v[248:249]
	v_pk_mul_f32 v[12:13], v[12:13], v[250:251]
	v_pk_mul_f32 v[14:15], v[14:15], v[252:253]
	v_cvt_pk_bf16_f32 v226, v16, v17
	v_cvt_pk_bf16_f32 v227, v18, v19
	v_cvt_pk_bf16_f32 v228, v12, v13
	v_cvt_pk_bf16_f32 v229, v14, v15
	global_store_dwordx4 v144, v[226:229], s[42:43] offset:64
	v_add_u32_e32 v0, v153, v145
	s_waitcnt vmcnt(15)
	v_cvt_f32_ubyte0_e32 v246, v202
	v_cvt_f32_ubyte1_e32 v247, v202
	v_cvt_f32_ubyte2_e32 v248, v202
	v_cvt_f32_ubyte3_e32 v249, v202
	v_cvt_f32_ubyte0_e32 v250, v203
	v_cvt_f32_ubyte1_e32 v251, v203
	v_cvt_f32_ubyte2_e32 v252, v203
	v_cvt_f32_ubyte3_e32 v253, v203
	v_max_f32_e32 v246, 0.5, v246
	v_max_f32_e32 v247, 0.5, v247
	v_max_f32_e32 v248, 0.5, v248
	v_max_f32_e32 v249, 0.5, v249
	v_max_f32_e32 v250, 0.5, v250
	v_max_f32_e32 v251, 0.5, v251
	v_max_f32_e32 v252, 0.5, v252
	v_max_f32_e32 v253, 0.5, v253
	v_pk_mul_f32 v[246:247], v[246:247], s[28:29] op_sel_hi:[1,0]
	v_pk_mul_f32 v[248:249], v[248:249], s[28:29] op_sel_hi:[1,0]
	v_pk_mul_f32 v[250:251], v[250:251], s[28:29] op_sel_hi:[1,0]
	v_pk_mul_f32 v[252:253], v[252:253], s[28:29] op_sel_hi:[1,0]
	v_pk_mul_f32 v[40:41], v[40:41], v[246:247]
	v_pk_mul_f32 v[42:43], v[42:43], v[248:249]
	v_pk_mul_f32 v[36:37], v[36:37], v[250:251]
	v_pk_mul_f32 v[38:39], v[38:39], v[252:253]
	v_cvt_pk_bf16_f32 v230, v40, v41
	v_cvt_pk_bf16_f32 v231, v42, v43
	v_cvt_pk_bf16_f32 v232, v36, v37
	v_cvt_pk_bf16_f32 v233, v38, v39
	global_store_dwordx4 v0, v[230:233], s[42:43]
	s_waitcnt vmcnt(15)
	v_cvt_f32_ubyte0_e32 v246, v204
	v_cvt_f32_ubyte1_e32 v247, v204
	v_cvt_f32_ubyte2_e32 v248, v204
	v_cvt_f32_ubyte3_e32 v249, v204
	v_cvt_f32_ubyte0_e32 v250, v205
	v_cvt_f32_ubyte1_e32 v251, v205
	v_cvt_f32_ubyte2_e32 v252, v205
	v_cvt_f32_ubyte3_e32 v253, v205
	v_max_f32_e32 v246, 0.5, v246
	v_max_f32_e32 v247, 0.5, v247
	v_max_f32_e32 v248, 0.5, v248
	v_max_f32_e32 v249, 0.5, v249
	v_max_f32_e32 v250, 0.5, v250
	v_max_f32_e32 v251, 0.5, v251
	v_max_f32_e32 v252, 0.5, v252
	v_max_f32_e32 v253, 0.5, v253
	v_pk_mul_f32 v[246:247], v[246:247], s[28:29] op_sel_hi:[1,0]
	v_pk_mul_f32 v[248:249], v[248:249], s[28:29] op_sel_hi:[1,0]
	v_pk_mul_f32 v[250:251], v[250:251], s[28:29] op_sel_hi:[1,0]
	v_pk_mul_f32 v[252:253], v[252:253], s[28:29] op_sel_hi:[1,0]
	v_pk_mul_f32 v[8:9], v[8:9], v[246:247]
	v_pk_mul_f32 v[10:11], v[10:11], v[248:249]
	v_pk_mul_f32 v[4:5], v[4:5], v[250:251]
	v_pk_mul_f32 v[6:7], v[6:7], v[252:253]
	v_cvt_pk_bf16_f32 v234, v8, v9
	v_cvt_pk_bf16_f32 v235, v10, v11
	v_cvt_pk_bf16_f32 v236, v4, v5
	v_cvt_pk_bf16_f32 v237, v6, v7
	global_store_dwordx4 v0, v[234:237], s[42:43] offset:64
	s_mov_b64 s[40:41], 0
; #define PG8_BAR __builtin_amdgcn_s_barrier()
; template <class Epi, class SchedT, bool ALIGN_EPI, bool SP2>
; __device__ __forceinline__ void gemm_phase(LAS unsigned char* lds, const int ldk, const int nt, const SchedT& S, const Epi& E) {
;     ...
;         if (!has_next) break;
;         if (!(SchedT::kMode == 2 && cur.kind == 0)) {
; #pragma unroll
;         for (int a = 0; a < 2; ++a)
; #pragma unroll
;             for (int b = 0; b < 2; ++b)
; #pragma unroll
;                 for (int m = 0; m < 4; ++m)
; #pragma unroll
;                     for (int n = 0; n < 2; ++n) acc[a][b][m][n] = (f32x4){0.f, 0.f, 0.f, 0.f};
;         }
;         cur = nxt; cA = nA; cB = nB; ++ui;
;         if constexpr (ALIGN_EPI) { if (wr == 1) PG8_BAR; }
;     }
.Lp3e_done:
.LBB0_585:
	s_and_b64 vcc, exec, s[38:39]
	s_mov_b64 s[12:13], -1
	s_cbranch_vccnz .LBB0_528
	s_and_b64 vcc, exec, s[40:41]
	s_cbranch_vccnz .LBB0_588
	v_mov_b32_e32 v2, v1
	v_mov_b32_e32 v3, v1
	v_mov_b32_e32 v0, v1
	v_mov_b64_e32 v[6:7], v[2:3]
	v_mov_b64_e32 v[10:11], v[2:3]
	v_mov_b64_e32 v[14:15], v[2:3]
	v_mov_b64_e32 v[18:19], v[2:3]
	v_mov_b64_e32 v[22:23], v[2:3]
	v_mov_b64_e32 v[26:27], v[2:3]
	v_mov_b64_e32 v[30:31], v[2:3]
	v_mov_b64_e32 v[34:35], v[2:3]
	v_mov_b64_e32 v[38:39], v[2:3]
	v_mov_b64_e32 v[42:43], v[2:3]
	v_mov_b64_e32 v[46:47], v[2:3]
	v_mov_b64_e32 v[50:51], v[2:3]
	v_mov_b64_e32 v[54:55], v[2:3]
	v_mov_b64_e32 v[58:59], v[2:3]
	v_mov_b64_e32 v[62:63], v[2:3]
	v_mov_b64_e32 v[66:67], v[2:3]
	v_mov_b64_e32 v[70:71], v[2:3]
	v_mov_b64_e32 v[74:75], v[2:3]
	v_mov_b64_e32 v[78:79], v[2:3]
	v_mov_b64_e32 v[82:83], v[2:3]
	v_mov_b64_e32 v[86:87], v[2:3]
	v_mov_b64_e32 v[90:91], v[2:3]
	v_mov_b64_e32 v[94:95], v[2:3]
	v_mov_b64_e32 v[98:99], v[2:3]
	v_mov_b64_e32 v[102:103], v[2:3]
	v_mov_b64_e32 v[106:107], v[2:3]
	v_mov_b64_e32 v[110:111], v[2:3]
	v_mov_b64_e32 v[114:115], v[2:3]
	v_mov_b64_e32 v[118:119], v[2:3]
	v_mov_b64_e32 v[122:123], v[2:3]
	v_mov_b64_e32 v[126:127], v[2:3]
	v_mov_b64_e32 v[130:131], v[2:3]
	v_mov_b64_e32 v[4:5], v[0:1]
	v_mov_b64_e32 v[8:9], v[0:1]
	v_mov_b64_e32 v[12:13], v[0:1]
	v_mov_b64_e32 v[16:17], v[0:1]
	v_mov_b64_e32 v[20:21], v[0:1]
	v_mov_b64_e32 v[24:25], v[0:1]
	v_mov_b64_e32 v[28:29], v[0:1]
	v_mov_b64_e32 v[32:33], v[0:1]
	v_mov_b64_e32 v[36:37], v[0:1]
	v_mov_b64_e32 v[40:41], v[0:1]
	v_mov_b64_e32 v[44:45], v[0:1]
	v_mov_b64_e32 v[48:49], v[0:1]
	v_mov_b64_e32 v[52:53], v[0:1]
	v_mov_b64_e32 v[56:57], v[0:1]
	v_mov_b64_e32 v[60:61], v[0:1]
	v_mov_b64_e32 v[64:65], v[0:1]
	v_mov_b64_e32 v[68:69], v[0:1]
	v_mov_b64_e32 v[72:73], v[0:1]
	v_mov_b64_e32 v[76:77], v[0:1]
	v_mov_b64_e32 v[80:81], v[0:1]
	v_mov_b64_e32 v[84:85], v[0:1]
	v_mov_b64_e32 v[88:89], v[0:1]
	v_mov_b64_e32 v[92:93], v[0:1]
	v_mov_b64_e32 v[96:97], v[0:1]
	v_mov_b64_e32 v[100:101], v[0:1]
	v_mov_b64_e32 v[104:105], v[0:1]
	v_mov_b64_e32 v[108:109], v[0:1]
	v_mov_b64_e32 v[112:113], v[0:1]
	v_mov_b64_e32 v[116:117], v[0:1]
	v_mov_b64_e32 v[120:121], v[0:1]
	v_mov_b64_e32 v[124:125], v[0:1]
	v_mov_b64_e32 v[128:129], v[0:1]
.LBB0_588:
	s_andn2_b64 vcc, exec, s[18:19]
	s_cbranch_vccnz .LBB0_527
	s_barrier
	s_branch .LBB0_527
.LBB0_606:
	s_waitcnt vmcnt(0)
	v_readlane_b32 s60, v163, 31
	v_readlane_b32 s61, v163, 32
	s_barrier
